# sample attention score pass rewritten: 16 lanes per f32 K-cache row (coalesced) + the 4 token steps of one (batch, head) on adjacent waves; plus QKV tile balance, S5 XCD remap, global stores
# speedup vs baseline: 1.0668x; 1.0151x over previous
; #define LAS __attribute__((address_space(3)))
; DI float bflo(unsigned w) { return __uint_as_float(w << 16); }
; DI float bfhi(unsigned w) { return __uint_as_float(w & 0xffff0000u); }
; DI float bf2f(bf16_t b) { return __uint_as_float((unsigned)b << 16); }
; #define LDS_WAIT() asm volatile("s_waitcnt lgkmcnt(0)" ::: "memory")
; DI void attn_sample_unit(const Params& p, int u, const bf16_t* Q, const bf16_t* Kb, const bf16_t* Vb, bf16_t* att, LAS float* sl, int lane) {
;     const int h = u & 15, t = (u >> 4) & 3, b = u >> 6;
;     const size_t qrow = (size_t)NP + b * 4 + t;
;     const float* ck = p.in[4]; const float* cv = p.in[5];
;     sl[lane] = bf2f(Q[qrow * 1024 + h * 64 + lane]);
;     LDS_WAIT();
;     float mx = -INFINITY;
; #pragma unroll 1
;     for (int e = 0; e < 9; ++e) { const int pat = e / 3, r = e - 3 * pat; const int dil = 1 << (2 * pat);
;         const int j = lane + 64 * r; const bool valid = j <= 128; const int idx = 2048 + t - dil * (valid ? j : 0);
;         float dot = 0.f;
;         if (idx >= 2048) { const bf16_t* kp = Kb + ((size_t)NP + b * 4 + (idx - 2048)) * 1024 + h * 64;
; #pragma unroll
;             for (int d8 = 0; d8 < 8; ++d8) { const u32x4 kw = *(const u32x4*)(kp + 8 * d8); const f32x4 q0 = *(const LAS f32x4*)(sl + 8 * d8), q1 = *(const LAS f32x4*)(sl + 8 * d8 + 4);
;                 dot += (bflo(kw.x) * q0[0] + bfhi(kw.x) * q0[1]) + (bflo(kw.y) * q0[2] + bfhi(kw.y) * q0[3]) + (bflo(kw.z) * q1[0] + bfhi(kw.z) * q1[1]) + (bflo(kw.w) * q1[2] + bfhi(kw.w) * q1[3]); } }
;         else { const float* kp = ck + (((size_t)b * 2048 + idx) * 16 + h) * 64;
; #pragma unroll
;             for (int d4 = 0; d4 < 16; ++d4) { const f32x4 kv = *(const f32x4*)(kp + 4 * d4); const f32x4 qv = *(const LAS f32x4*)(sl + 4 * d4); dot += (kv[0] * qv[0] + kv[1] * qv[1]) + (kv[2] * qv[2] + kv[3] * qv[3]); } }
;         if (valid) { sl[64 + pat * 192 + j] = dot; mx = fmaxf(mx, dot); } }
.LBB0_1521:
	s_ashr_i32 s86, s80, 6
	s_lshl_b32 s0, s86, 2
	s_add_i32 s0, s0, 0x8000
	s_and_b32 s4, s80, 3
	s_ashr_i32 s1, s0, 31
	s_or_b32 s76, s0, s4
	s_mov_b32 s77, s1
	s_lshl_b64 s[78:79], s[76:77], 10
	s_bfe_u32 s5, s80, 0x40002
	v_writelane_b32 v254, s78, 12
	s_lshl_b32 s2, s5, 6
	s_lshl_b64 s[76:77], s[76:77], 11
	v_writelane_b32 v254, s79, 13
	v_writelane_b32 v254, s2, 10
	s_mov_b32 s90, s82
	v_readlane_b32 s78, v254, 6
	v_readlane_b32 s79, v254, 7
	s_add_u32 s2, s78, s76
	s_addc_u32 s77, s79, s77
	s_lshl_b32 s78, s5, 7
	s_add_u32 s76, s2, s78
	s_addc_u32 s77, s77, 0
	v_lshl_add_u64 v[0:1], v[128:129], 1, s[76:77]
	global_load_ushort v0, v[0:1], off
	s_or_b32 s2, s4, 0x800
	s_add_u32 s88, s96, s78
	s_addc_u32 s89, s97, 0
	s_ashr_i32 s87, s86, 31
	s_lshl_b32 s78, s5, 8
	s_lshl_b64 s[76:77], s[86:87], 23
	v_readlane_b32 s92, v254, 14
	v_readlane_b32 s93, v254, 15
	s_add_u32 s76, s92, s76
	s_addc_u32 s77, s93, s77
	v_readlane_b32 s94, v254, 16
	s_add_u32 s84, s76, s78
	s_addc_u32 s85, s77, 0
	v_mov_b32_e32 v40, 0xff800000
	v_mov_b32_e32 v41, v128
	v_mov_b32_e32 v42, v210
	s_mov_b32 s94, 0
	v_readlane_b32 s95, v254, 17
	s_waitcnt vmcnt(0)
	v_lshlrev_b32_e32 v0, 16, v0
	ds_write_b32 v145, v0
	s_waitcnt lgkmcnt(0)
	v_lshrrev_b32_e32 v41, 4, v128
	v_and_b32_e32 v42, 15, v128
	v_lshlrev_b32_e32 v43, 4, v42
	v_add_u32_e32 v51, s3, v43
	ds_read_b128 v[44:47], v51
	v_lshlrev_b32_e32 v48, 2, v41
	v_add_u32_e32 v48, s3, v48
	v_add_u32_e32 v48, 0x100, v48
	s_mov_b32 s100, 0x10001
	s_mov_b32 s101, 0x10001
	s_sub_i32 s1, 3, s4
	s_lshl_b32 s1, s1, 4
	s_lshr_b64 s[100:101], s[100:101], s1
	s_mov_b32 s98, 0x10001
	s_mov_b32 s99, 0x10001
	s_xor_b64 s[98:99], s[98:99], s[100:101]
	s_lshl_b32 s1, s0, 11
	s_add_u32 s94, s88, s1
	s_addc_u32 s95, s89, 0
	v_lshlrev_b32_e32 v102, 11, v41
	v_lshl_add_u32 v102, v42, 3, v102
	global_load_dwordx2 v[100:101], v102, s[94:95]
	s_waitcnt lgkmcnt(0)
	v_lshlrev_b32_e32 v49, 0, v41
	v_sub_u32_e32 v49, s2, v49
	v_min_i32_e32 v50, 0x7ff, v49
	v_lshl_add_u32 v49, v49, 12, v43
	v_lshl_add_u32 v50, v50, 12, v43
	s_mov_b64 s[76:77], s[84:85]
	global_load_dwordx4 v[0:3], v50, s[76:77]
	s_sub_u32 s76, s76, 0x4000
	s_subb_u32 s77, s77, 0
	global_load_dwordx4 v[4:7], v49, s[76:77]
	s_sub_u32 s76, s76, 0x4000
	s_subb_u32 s77, s77, 0
	global_load_dwordx4 v[8:11], v49, s[76:77]
	s_sub_u32 s76, s76, 0x4000
	s_subb_u32 s77, s77, 0
	global_load_dwordx4 v[12:15], v49, s[76:77]
	s_sub_u32 s76, s76, 0x4000
	s_subb_u32 s77, s77, 0
	global_load_dwordx4 v[16:19], v49, s[76:77]
	s_sub_u32 s76, s76, 0x4000
	s_subb_u32 s77, s77, 0
	global_load_dwordx4 v[20:23], v49, s[76:77]
	s_sub_u32 s76, s76, 0x4000
	s_subb_u32 s77, s77, 0
	global_load_dwordx4 v[24:27], v49, s[76:77]
	s_sub_u32 s76, s76, 0x4000
	s_subb_u32 s77, s77, 0
	global_load_dwordx4 v[28:31], v49, s[76:77]
	s_sub_u32 s76, s76, 0x4000
	s_subb_u32 s77, s77, 0
	global_load_dwordx4 v[32:35], v49, s[76:77]
	s_sub_u32 s76, s76, 0x4000
	s_subb_u32 s77, s77, 0
	global_load_dwordx4 v[36:39], v49, s[76:77]
	s_sub_u32 s76, s76, 0x4000
	s_subb_u32 s77, s77, 0
	global_load_dwordx4 v[52:55], v49, s[76:77]
	s_sub_u32 s76, s76, 0x4000
	s_subb_u32 s77, s77, 0
	global_load_dwordx4 v[56:59], v49, s[76:77]
	s_sub_u32 s76, s76, 0x4000
	s_subb_u32 s77, s77, 0
	global_load_dwordx4 v[60:63], v49, s[76:77]
	s_sub_u32 s76, s76, 0x4000
	s_subb_u32 s77, s77, 0
	global_load_dwordx4 v[64:67], v49, s[76:77]
	s_sub_u32 s76, s76, 0x4000
	s_subb_u32 s77, s77, 0
	global_load_dwordx4 v[68:71], v49, s[76:77]
	s_sub_u32 s76, s76, 0x4000
	s_subb_u32 s77, s77, 0
	global_load_dwordx4 v[72:75], v49, s[76:77]
	s_sub_u32 s76, s76, 0x4000
	s_subb_u32 s77, s77, 0
	global_load_dwordx4 v[76:79], v49, s[76:77]
	s_sub_u32 s76, s76, 0x4000
	s_subb_u32 s77, s77, 0
	global_load_dwordx4 v[80:83], v49, s[76:77]
	s_sub_u32 s76, s76, 0x4000
	s_subb_u32 s77, s77, 0
	global_load_dwordx4 v[84:87], v49, s[76:77]
	s_sub_u32 s76, s76, 0x4000
	s_subb_u32 s77, s77, 0
	global_load_dwordx4 v[88:91], v49, s[76:77]
	s_sub_u32 s76, s76, 0x4000
	s_subb_u32 s77, s77, 0
	global_load_dwordx4 v[92:95], v49, s[76:77]
	s_sub_u32 s76, s76, 0x4000
	s_subb_u32 s77, s77, 0
	global_load_dwordx4 v[96:99], v49, s[76:77]
	s_sub_u32 s76, s76, 0x4000
	s_subb_u32 s77, s77, 0
	s_waitcnt vmcnt(11)
; #define LAS __attribute__((address_space(3)))
; DI float bflo(unsigned w) { return __uint_as_float(w << 16); }
; DI float bfhi(unsigned w) { return __uint_as_float(w & 0xffff0000u); }
; DI void attn_sample_unit(const Params& p, int u, const bf16_t* Q, const bf16_t* Kb, const bf16_t* Vb, bf16_t* att, LAS float* sl, int lane) {
;     ...
;     for (int e = 0; e < 9; ++e) { const int pat = e / 3, r = e - 3 * pat; const int dil = 1 << (2 * pat);
;         const int j = lane + 64 * r; const bool valid = j <= 128; const int idx = 2048 + t - dil * (valid ? j : 0);
;         float dot = 0.f;
;         if (idx >= 2048) { const bf16_t* kp = Kb + ((size_t)NP + b * 4 + (idx - 2048)) * 1024 + h * 64;
; #pragma unroll
;             for (int d8 = 0; d8 < 8; ++d8) { const u32x4 kw = *(const u32x4*)(kp + 8 * d8); const f32x4 q0 = *(const LAS f32x4*)(sl + 8 * d8), q1 = *(const LAS f32x4*)(sl + 8 * d8 + 4);
;                 dot += (bflo(kw.x) * q0[0] + bfhi(kw.x) * q0[1]) + (bflo(kw.y) * q0[2] + bfhi(kw.y) * q0[3]) + (bflo(kw.z) * q1[0] + bfhi(kw.z) * q1[1]) + (bflo(kw.w) * q1[2] + bfhi(kw.w) * q1[3]); } }
;         else { const float* kp = ck + (((size_t)b * 2048 + idx) * 16 + h) * 64;
; #pragma unroll
;             for (int d4 = 0; d4 < 16; ++d4) { const f32x4 kv = *(const f32x4*)(kp + 4 * d4); const f32x4 qv = *(const LAS f32x4*)(sl + 4 * d4); dot += (kv[0] * qv[0] + kv[1] * qv[1]) + (kv[2] * qv[2] + kv[3] * qv[3]); } }
;         if (valid) { sl[64 + pat * 192 + j] = dot; mx = fmaxf(mx, dot); } }
	v_lshlrev_b32_e32 v104, 16, v100
	v_and_b32_e32 v105, 0xffff0000, v100
	v_lshlrev_b32_e32 v106, 16, v101
	v_and_b32_e32 v107, 0xffff0000, v101
	v_mul_f32_e32 v104, v104, v44
	v_fmac_f32_e32 v104, v105, v45
	v_fmac_f32_e32 v104, v106, v46
	v_fmac_f32_e32 v104, v107, v47
	s_nop 1
	v_add_f32_dpp v104, v104, v104 quad_perm:[1,0,3,2] row_mask:0xf bank_mask:0xf
	s_nop 1
	v_add_f32_dpp v104, v104, v104 quad_perm:[2,3,0,1] row_mask:0xf bank_mask:0xf
	s_nop 1
	v_add_f32_dpp v104, v104, v104 row_half_mirror row_mask:0xf bank_mask:0xf
	s_nop 1
	v_add_f32_dpp v104, v104, v104 row_mirror row_mask:0xf bank_mask:0xf
	s_lshl_b32 s1, s4, 2
	s_add_i32 s1, s1, s3
	s_addk_i32 s1, 0x100
	v_lshlrev_b32_e32 v108, 2, v41
	v_sub_u32_e32 v108, s1, v108
	v_mov_b32_e32 v109, s3
	s_mov_b64 exec, s[100:101]
	ds_write_b32 v108, v104
	v_max_f32_e32 v40, v40, v104
	s_lshl_b32 s1, s4, 4
	s_lshl_b64 s[82:83], 1, s1
	s_mov_b64 exec, s[82:83]
	ds_write_b32 v109, v104 offset:1024
	ds_write_b32 v109, v104 offset:1792
	s_mov_b64 exec, -1
	s_nop 4
	v_mul_f32_e32 v0, v0, v44
	v_mul_f32_e32 v4, v4, v44
	v_mul_f32_e32 v8, v8, v44
	v_mul_f32_e32 v12, v12, v44
	v_mul_f32_e32 v16, v16, v44
	v_mul_f32_e32 v20, v20, v44
	v_mul_f32_e32 v24, v24, v44
	v_mul_f32_e32 v28, v28, v44
	v_mul_f32_e32 v32, v32, v44
	v_mul_f32_e32 v36, v36, v44
	v_mul_f32_e32 v52, v52, v44
	v_fmac_f32_e32 v0, v1, v45
	v_fmac_f32_e32 v4, v5, v45
	v_fmac_f32_e32 v8, v9, v45
	v_fmac_f32_e32 v12, v13, v45
	v_fmac_f32_e32 v16, v17, v45
	v_fmac_f32_e32 v20, v21, v45
	v_fmac_f32_e32 v24, v25, v45
	v_fmac_f32_e32 v28, v29, v45
	v_fmac_f32_e32 v32, v33, v45
	v_fmac_f32_e32 v36, v37, v45
	v_fmac_f32_e32 v52, v53, v45
	v_fmac_f32_e32 v0, v2, v46
	v_fmac_f32_e32 v4, v6, v46
	v_fmac_f32_e32 v8, v10, v46
	v_fmac_f32_e32 v12, v14, v46
	v_fmac_f32_e32 v16, v18, v46
	v_fmac_f32_e32 v20, v22, v46
	v_fmac_f32_e32 v24, v26, v46
	v_fmac_f32_e32 v28, v30, v46
	v_fmac_f32_e32 v32, v34, v46
	v_fmac_f32_e32 v36, v38, v46
	v_fmac_f32_e32 v52, v54, v46
	v_fmac_f32_e32 v0, v3, v47
	v_fmac_f32_e32 v4, v7, v47
	v_fmac_f32_e32 v8, v11, v47
	v_fmac_f32_e32 v12, v15, v47
	v_fmac_f32_e32 v16, v19, v47
	v_fmac_f32_e32 v20, v23, v47
	v_fmac_f32_e32 v24, v27, v47
	v_fmac_f32_e32 v28, v31, v47
	v_fmac_f32_e32 v32, v35, v47
	v_fmac_f32_e32 v36, v39, v47
	v_fmac_f32_e32 v52, v55, v47
	s_nop 1
	v_add_f32_dpp v0, v0, v0 quad_perm:[1,0,3,2] row_mask:0xf bank_mask:0xf
	v_add_f32_dpp v4, v4, v4 quad_perm:[1,0,3,2] row_mask:0xf bank_mask:0xf
	v_add_f32_dpp v8, v8, v8 quad_perm:[1,0,3,2] row_mask:0xf bank_mask:0xf
	v_add_f32_dpp v12, v12, v12 quad_perm:[1,0,3,2] row_mask:0xf bank_mask:0xf
	v_add_f32_dpp v16, v16, v16 quad_perm:[1,0,3,2] row_mask:0xf bank_mask:0xf
	v_add_f32_dpp v20, v20, v20 quad_perm:[1,0,3,2] row_mask:0xf bank_mask:0xf
	v_add_f32_dpp v24, v24, v24 quad_perm:[1,0,3,2] row_mask:0xf bank_mask:0xf
	v_add_f32_dpp v28, v28, v28 quad_perm:[1,0,3,2] row_mask:0xf bank_mask:0xf
	v_add_f32_dpp v32, v32, v32 quad_perm:[1,0,3,2] row_mask:0xf bank_mask:0xf
	v_add_f32_dpp v36, v36, v36 quad_perm:[1,0,3,2] row_mask:0xf bank_mask:0xf
	v_add_f32_dpp v52, v52, v52 quad_perm:[1,0,3,2] row_mask:0xf bank_mask:0xf
	s_nop 1
	v_add_f32_dpp v0, v0, v0 quad_perm:[2,3,0,1] row_mask:0xf bank_mask:0xf
	v_add_f32_dpp v4, v4, v4 quad_perm:[2,3,0,1] row_mask:0xf bank_mask:0xf
	v_add_f32_dpp v8, v8, v8 quad_perm:[2,3,0,1] row_mask:0xf bank_mask:0xf
	v_add_f32_dpp v12, v12, v12 quad_perm:[2,3,0,1] row_mask:0xf bank_mask:0xf
	v_add_f32_dpp v16, v16, v16 quad_perm:[2,3,0,1] row_mask:0xf bank_mask:0xf
	v_add_f32_dpp v20, v20, v20 quad_perm:[2,3,0,1] row_mask:0xf bank_mask:0xf
	v_add_f32_dpp v24, v24, v24 quad_perm:[2,3,0,1] row_mask:0xf bank_mask:0xf
	v_add_f32_dpp v28, v28, v28 quad_perm:[2,3,0,1] row_mask:0xf bank_mask:0xf
	v_add_f32_dpp v32, v32, v32 quad_perm:[2,3,0,1] row_mask:0xf bank_mask:0xf
	v_add_f32_dpp v36, v36, v36 quad_perm:[2,3,0,1] row_mask:0xf bank_mask:0xf
	v_add_f32_dpp v52, v52, v52 quad_perm:[2,3,0,1] row_mask:0xf bank_mask:0xf
	s_nop 1
	v_add_f32_dpp v0, v0, v0 row_half_mirror row_mask:0xf bank_mask:0xf
	v_add_f32_dpp v4, v4, v4 row_half_mirror row_mask:0xf bank_mask:0xf
	v_add_f32_dpp v8, v8, v8 row_half_mirror row_mask:0xf bank_mask:0xf
	v_add_f32_dpp v12, v12, v12 row_half_mirror row_mask:0xf bank_mask:0xf
	v_add_f32_dpp v16, v16, v16 row_half_mirror row_mask:0xf bank_mask:0xf
	v_add_f32_dpp v20, v20, v20 row_half_mirror row_mask:0xf bank_mask:0xf
	v_add_f32_dpp v24, v24, v24 row_half_mirror row_mask:0xf bank_mask:0xf
	v_add_f32_dpp v28, v28, v28 row_half_mirror row_mask:0xf bank_mask:0xf
	v_add_f32_dpp v32, v32, v32 row_half_mirror row_mask:0xf bank_mask:0xf
	v_add_f32_dpp v36, v36, v36 row_half_mirror row_mask:0xf bank_mask:0xf
	v_add_f32_dpp v52, v52, v52 row_half_mirror row_mask:0xf bank_mask:0xf
	s_nop 1
	v_add_f32_dpp v0, v0, v0 row_mirror row_mask:0xf bank_mask:0xf
	v_add_f32_dpp v4, v4, v4 row_mirror row_mask:0xf bank_mask:0xf
	v_add_f32_dpp v8, v8, v8 row_mirror row_mask:0xf bank_mask:0xf
	v_add_f32_dpp v12, v12, v12 row_mirror row_mask:0xf bank_mask:0xf
	v_add_f32_dpp v16, v16, v16 row_mirror row_mask:0xf bank_mask:0xf
	v_add_f32_dpp v20, v20, v20 row_mirror row_mask:0xf bank_mask:0xf
	v_add_f32_dpp v24, v24, v24 row_mirror row_mask:0xf bank_mask:0xf
	v_add_f32_dpp v28, v28, v28 row_mirror row_mask:0xf bank_mask:0xf
	v_add_f32_dpp v32, v32, v32 row_mirror row_mask:0xf bank_mask:0xf
	v_add_f32_dpp v36, v36, v36 row_mirror row_mask:0xf bank_mask:0xf
	v_add_f32_dpp v52, v52, v52 row_mirror row_mask:0xf bank_mask:0xf
	s_nop 1
	s_mov_b64 exec, s[98:99]
	ds_write_b32 v48, v0 offset:0
	v_max_f32_e32 v40, v40, v0
	s_mov_b32 s82, 0x10001
; #define LAS __attribute__((address_space(3)))
; DI float bflo(unsigned w) { return __uint_as_float(w << 16); }
; DI float bfhi(unsigned w) { return __uint_as_float(w & 0xffff0000u); }
; DI void attn_sample_unit(const Params& p, int u, const bf16_t* Q, const bf16_t* Kb, const bf16_t* Vb, bf16_t* att, LAS float* sl, int lane) {
;     ...
;     for (int e = 0; e < 9; ++e) { const int pat = e / 3, r = e - 3 * pat; const int dil = 1 << (2 * pat);
;         const int j = lane + 64 * r; const bool valid = j <= 128; const int idx = 2048 + t - dil * (valid ? j : 0);
;         float dot = 0.f;
;         if (idx >= 2048) { const bf16_t* kp = Kb + ((size_t)NP + b * 4 + (idx - 2048)) * 1024 + h * 64;
; #pragma unroll
;             for (int d8 = 0; d8 < 8; ++d8) { const u32x4 kw = *(const u32x4*)(kp + 8 * d8); const f32x4 q0 = *(const LAS f32x4*)(sl + 8 * d8), q1 = *(const LAS f32x4*)(sl + 8 * d8 + 4);
;                 dot += (bflo(kw.x) * q0[0] + bfhi(kw.x) * q0[1]) + (bflo(kw.y) * q0[2] + bfhi(kw.y) * q0[3]) + (bflo(kw.z) * q1[0] + bfhi(kw.z) * q1[1]) + (bflo(kw.w) * q1[2] + bfhi(kw.w) * q1[3]); } }
;         else { const float* kp = ck + (((size_t)b * 2048 + idx) * 16 + h) * 64;
; #pragma unroll
;             for (int d4 = 0; d4 < 16; ++d4) { const f32x4 kv = *(const f32x4*)(kp + 4 * d4); const f32x4 qv = *(const LAS f32x4*)(sl + 4 * d4); dot += (kv[0] * qv[0] + kv[1] * qv[1]) + (kv[2] * qv[2] + kv[3] * qv[3]); } }
;         if (valid) { sl[64 + pat * 192 + j] = dot; mx = fmaxf(mx, dot); } }
	s_mov_b32 s83, 0x10001
	s_mov_b64 exec, s[82:83]
	ds_write_b32 v48, v4 offset:16
	v_max_f32_e32 v40, v40, v4
	ds_write_b32 v48, v8 offset:32
	v_max_f32_e32 v40, v40, v8
	ds_write_b32 v48, v12 offset:48
	v_max_f32_e32 v40, v40, v12
	ds_write_b32 v48, v16 offset:64
	v_max_f32_e32 v40, v40, v16
	ds_write_b32 v48, v20 offset:80
	v_max_f32_e32 v40, v40, v20
	ds_write_b32 v48, v24 offset:96
	v_max_f32_e32 v40, v40, v24
	ds_write_b32 v48, v28 offset:112
	v_max_f32_e32 v40, v40, v28
	ds_write_b32 v48, v32 offset:128
	v_max_f32_e32 v40, v40, v32
	ds_write_b32 v48, v36 offset:144
	v_max_f32_e32 v40, v40, v36
	ds_write_b32 v48, v52 offset:160
	v_max_f32_e32 v40, v40, v52
	s_mov_b64 exec, -1
	s_nop 4
	global_load_dwordx4 v[0:3], v49, s[76:77]
	s_sub_u32 s76, s76, 0x4000
	s_subb_u32 s77, s77, 0
	global_load_dwordx4 v[4:7], v49, s[76:77]
	s_sub_u32 s76, s76, 0x4000
	s_subb_u32 s77, s77, 0
	global_load_dwordx4 v[8:11], v49, s[76:77]
	s_sub_u32 s76, s76, 0x4000
	s_subb_u32 s77, s77, 0
	global_load_dwordx4 v[12:15], v49, s[76:77]
	s_sub_u32 s76, s76, 0x4000
	s_subb_u32 s77, s77, 0
	global_load_dwordx4 v[16:19], v49, s[76:77]
	s_sub_u32 s76, s76, 0x4000
	s_subb_u32 s77, s77, 0
	global_load_dwordx4 v[20:23], v49, s[76:77]
	s_sub_u32 s76, s76, 0x4000
	s_subb_u32 s77, s77, 0
	global_load_dwordx4 v[24:27], v49, s[76:77]
	s_sub_u32 s76, s76, 0x4000
	s_subb_u32 s77, s77, 0
	global_load_dwordx4 v[28:31], v49, s[76:77]
	s_sub_u32 s76, s76, 0x4000
	s_subb_u32 s77, s77, 0
	global_load_dwordx4 v[32:35], v49, s[76:77]
	s_sub_u32 s76, s76, 0x4000
	s_subb_u32 s77, s77, 0
	global_load_dwordx4 v[36:39], v49, s[76:77]
	s_sub_u32 s76, s76, 0x4000
	s_subb_u32 s77, s77, 0
	s_mov_b64 exec, 0xffff
	global_load_dwordx4 v[52:55], v49, s[76:77]
	s_mov_b64 exec, -1
	s_waitcnt vmcnt(11)
	v_mul_f32_e32 v56, v56, v44
	v_mul_f32_e32 v60, v60, v44
	v_mul_f32_e32 v64, v64, v44
	v_mul_f32_e32 v68, v68, v44
	v_mul_f32_e32 v72, v72, v44
	v_mul_f32_e32 v76, v76, v44
	v_mul_f32_e32 v80, v80, v44
	v_mul_f32_e32 v84, v84, v44
	v_mul_f32_e32 v88, v88, v44
	v_mul_f32_e32 v92, v92, v44
	v_mul_f32_e32 v96, v96, v44
	v_fmac_f32_e32 v56, v57, v45
	v_fmac_f32_e32 v60, v61, v45
	v_fmac_f32_e32 v64, v65, v45
	v_fmac_f32_e32 v68, v69, v45
	v_fmac_f32_e32 v72, v73, v45
	v_fmac_f32_e32 v76, v77, v45
	v_fmac_f32_e32 v80, v81, v45
	v_fmac_f32_e32 v84, v85, v45
	v_fmac_f32_e32 v88, v89, v45
	v_fmac_f32_e32 v92, v93, v45
	v_fmac_f32_e32 v96, v97, v45
	v_fmac_f32_e32 v56, v58, v46
	v_fmac_f32_e32 v60, v62, v46
	v_fmac_f32_e32 v64, v66, v46
	v_fmac_f32_e32 v68, v70, v46
	v_fmac_f32_e32 v72, v74, v46
	v_fmac_f32_e32 v76, v78, v46
	v_fmac_f32_e32 v80, v82, v46
	v_fmac_f32_e32 v84, v86, v46
	v_fmac_f32_e32 v88, v90, v46
	v_fmac_f32_e32 v92, v94, v46
	v_fmac_f32_e32 v96, v98, v46
	v_fmac_f32_e32 v56, v59, v47
	v_fmac_f32_e32 v60, v63, v47
	v_fmac_f32_e32 v64, v67, v47
	v_fmac_f32_e32 v68, v71, v47
	v_fmac_f32_e32 v72, v75, v47
	v_fmac_f32_e32 v76, v79, v47
	v_fmac_f32_e32 v80, v83, v47
	v_fmac_f32_e32 v84, v87, v47
	v_fmac_f32_e32 v88, v91, v47
	v_fmac_f32_e32 v92, v95, v47
	v_fmac_f32_e32 v96, v99, v47
	s_nop 1
	v_add_f32_dpp v56, v56, v56 quad_perm:[1,0,3,2] row_mask:0xf bank_mask:0xf
	v_add_f32_dpp v60, v60, v60 quad_perm:[1,0,3,2] row_mask:0xf bank_mask:0xf
	v_add_f32_dpp v64, v64, v64 quad_perm:[1,0,3,2] row_mask:0xf bank_mask:0xf
	v_add_f32_dpp v68, v68, v68 quad_perm:[1,0,3,2] row_mask:0xf bank_mask:0xf
	v_add_f32_dpp v72, v72, v72 quad_perm:[1,0,3,2] row_mask:0xf bank_mask:0xf
	v_add_f32_dpp v76, v76, v76 quad_perm:[1,0,3,2] row_mask:0xf bank_mask:0xf
	v_add_f32_dpp v80, v80, v80 quad_perm:[1,0,3,2] row_mask:0xf bank_mask:0xf
	v_add_f32_dpp v84, v84, v84 quad_perm:[1,0,3,2] row_mask:0xf bank_mask:0xf
	v_add_f32_dpp v88, v88, v88 quad_perm:[1,0,3,2] row_mask:0xf bank_mask:0xf
	v_add_f32_dpp v92, v92, v92 quad_perm:[1,0,3,2] row_mask:0xf bank_mask:0xf
	v_add_f32_dpp v96, v96, v96 quad_perm:[1,0,3,2] row_mask:0xf bank_mask:0xf
	s_nop 1
	v_add_f32_dpp v56, v56, v56 quad_perm:[2,3,0,1] row_mask:0xf bank_mask:0xf
	v_add_f32_dpp v60, v60, v60 quad_perm:[2,3,0,1] row_mask:0xf bank_mask:0xf
	v_add_f32_dpp v64, v64, v64 quad_perm:[2,3,0,1] row_mask:0xf bank_mask:0xf
	v_add_f32_dpp v68, v68, v68 quad_perm:[2,3,0,1] row_mask:0xf bank_mask:0xf
	v_add_f32_dpp v72, v72, v72 quad_perm:[2,3,0,1] row_mask:0xf bank_mask:0xf
	v_add_f32_dpp v76, v76, v76 quad_perm:[2,3,0,1] row_mask:0xf bank_mask:0xf
	v_add_f32_dpp v80, v80, v80 quad_perm:[2,3,0,1] row_mask:0xf bank_mask:0xf
	v_add_f32_dpp v84, v84, v84 quad_perm:[2,3,0,1] row_mask:0xf bank_mask:0xf
	v_add_f32_dpp v88, v88, v88 quad_perm:[2,3,0,1] row_mask:0xf bank_mask:0xf
	v_add_f32_dpp v92, v92, v92 quad_perm:[2,3,0,1] row_mask:0xf bank_mask:0xf
	v_add_f32_dpp v96, v96, v96 quad_perm:[2,3,0,1] row_mask:0xf bank_mask:0xf
	s_nop 1
	v_add_f32_dpp v56, v56, v56 row_half_mirror row_mask:0xf bank_mask:0xf
	v_add_f32_dpp v60, v60, v60 row_half_mirror row_mask:0xf bank_mask:0xf
	v_add_f32_dpp v64, v64, v64 row_half_mirror row_mask:0xf bank_mask:0xf
	v_add_f32_dpp v68, v68, v68 row_half_mirror row_mask:0xf bank_mask:0xf
	v_add_f32_dpp v72, v72, v72 row_half_mirror row_mask:0xf bank_mask:0xf
	v_add_f32_dpp v76, v76, v76 row_half_mirror row_mask:0xf bank_mask:0xf
	v_add_f32_dpp v80, v80, v80 row_half_mirror row_mask:0xf bank_mask:0xf
	v_add_f32_dpp v84, v84, v84 row_half_mirror row_mask:0xf bank_mask:0xf
	v_add_f32_dpp v88, v88, v88 row_half_mirror row_mask:0xf bank_mask:0xf
	v_add_f32_dpp v92, v92, v92 row_half_mirror row_mask:0xf bank_mask:0xf
	v_add_f32_dpp v96, v96, v96 row_half_mirror row_mask:0xf bank_mask:0xf
	s_nop 1
	v_add_f32_dpp v56, v56, v56 row_mirror row_mask:0xf bank_mask:0xf
; #define LAS __attribute__((address_space(3)))
; DI float bflo(unsigned w) { return __uint_as_float(w << 16); }
; DI float bfhi(unsigned w) { return __uint_as_float(w & 0xffff0000u); }
; DI void attn_sample_unit(const Params& p, int u, const bf16_t* Q, const bf16_t* Kb, const bf16_t* Vb, bf16_t* att, LAS float* sl, int lane) {
;     ...
;     for (int e = 0; e < 9; ++e) { const int pat = e / 3, r = e - 3 * pat; const int dil = 1 << (2 * pat);
;         const int j = lane + 64 * r; const bool valid = j <= 128; const int idx = 2048 + t - dil * (valid ? j : 0);
;         float dot = 0.f;
;         if (idx >= 2048) { const bf16_t* kp = Kb + ((size_t)NP + b * 4 + (idx - 2048)) * 1024 + h * 64;
; #pragma unroll
;             for (int d8 = 0; d8 < 8; ++d8) { const u32x4 kw = *(const u32x4*)(kp + 8 * d8); const f32x4 q0 = *(const LAS f32x4*)(sl + 8 * d8), q1 = *(const LAS f32x4*)(sl + 8 * d8 + 4);
;                 dot += (bflo(kw.x) * q0[0] + bfhi(kw.x) * q0[1]) + (bflo(kw.y) * q0[2] + bfhi(kw.y) * q0[3]) + (bflo(kw.z) * q1[0] + bfhi(kw.z) * q1[1]) + (bflo(kw.w) * q1[2] + bfhi(kw.w) * q1[3]); } }
;         else { const float* kp = ck + (((size_t)b * 2048 + idx) * 16 + h) * 64;
; #pragma unroll
;             for (int d4 = 0; d4 < 16; ++d4) { const f32x4 kv = *(const f32x4*)(kp + 4 * d4); const f32x4 qv = *(const LAS f32x4*)(sl + 4 * d4); dot += (kv[0] * qv[0] + kv[1] * qv[1]) + (kv[2] * qv[2] + kv[3] * qv[3]); } }
;         if (valid) { sl[64 + pat * 192 + j] = dot; mx = fmaxf(mx, dot); } }
	v_add_f32_dpp v60, v60, v60 row_mirror row_mask:0xf bank_mask:0xf
	v_add_f32_dpp v64, v64, v64 row_mirror row_mask:0xf bank_mask:0xf
	v_add_f32_dpp v68, v68, v68 row_mirror row_mask:0xf bank_mask:0xf
	v_add_f32_dpp v72, v72, v72 row_mirror row_mask:0xf bank_mask:0xf
	v_add_f32_dpp v76, v76, v76 row_mirror row_mask:0xf bank_mask:0xf
	v_add_f32_dpp v80, v80, v80 row_mirror row_mask:0xf bank_mask:0xf
	v_add_f32_dpp v84, v84, v84 row_mirror row_mask:0xf bank_mask:0xf
	v_add_f32_dpp v88, v88, v88 row_mirror row_mask:0xf bank_mask:0xf
	v_add_f32_dpp v92, v92, v92 row_mirror row_mask:0xf bank_mask:0xf
	v_add_f32_dpp v96, v96, v96 row_mirror row_mask:0xf bank_mask:0xf
	s_nop 1
	s_mov_b32 s82, 0x10001
	s_mov_b32 s83, 0x10001
	s_mov_b64 exec, s[82:83]
	ds_write_b32 v48, v56 offset:176
	v_max_f32_e32 v40, v40, v56
	ds_write_b32 v48, v60 offset:192
	v_max_f32_e32 v40, v40, v60
	ds_write_b32 v48, v64 offset:208
	v_max_f32_e32 v40, v40, v64
	ds_write_b32 v48, v68 offset:224
	v_max_f32_e32 v40, v40, v68
	ds_write_b32 v48, v72 offset:240
	v_max_f32_e32 v40, v40, v72
	ds_write_b32 v48, v76 offset:256
	v_max_f32_e32 v40, v40, v76
	ds_write_b32 v48, v80 offset:272
	v_max_f32_e32 v40, v40, v80
	ds_write_b32 v48, v84 offset:288
	v_max_f32_e32 v40, v40, v84
	ds_write_b32 v48, v88 offset:304
	v_max_f32_e32 v40, v40, v88
	ds_write_b32 v48, v92 offset:320
	v_max_f32_e32 v40, v40, v92
	ds_write_b32 v48, v96 offset:336
	v_max_f32_e32 v40, v40, v96
	s_mov_b64 exec, -1
	s_nop 4
	v_lshlrev_b32_e32 v49, 2, v41
	v_sub_u32_e32 v49, s2, v49
	v_min_i32_e32 v50, 0x7ff, v49
	v_lshl_add_u32 v49, v49, 12, v43
	v_lshl_add_u32 v50, v50, 12, v43
	s_mov_b64 s[76:77], s[84:85]
	global_load_dwordx4 v[56:59], v50, s[76:77]
	s_sub_u32 s76, s76, 0x10000
	s_subb_u32 s77, s77, 0
	global_load_dwordx4 v[60:63], v49, s[76:77]
	s_sub_u32 s76, s76, 0x10000
	s_subb_u32 s77, s77, 0
	global_load_dwordx4 v[64:67], v49, s[76:77]
	s_sub_u32 s76, s76, 0x10000
	s_subb_u32 s77, s77, 0
	global_load_dwordx4 v[68:71], v49, s[76:77]
	s_sub_u32 s76, s76, 0x10000
	s_subb_u32 s77, s77, 0
	global_load_dwordx4 v[72:75], v49, s[76:77]
	s_sub_u32 s76, s76, 0x10000
	s_subb_u32 s77, s77, 0
	global_load_dwordx4 v[76:79], v49, s[76:77]
	s_sub_u32 s76, s76, 0x10000
	s_subb_u32 s77, s77, 0
	global_load_dwordx4 v[80:83], v49, s[76:77]
	s_sub_u32 s76, s76, 0x10000
	s_subb_u32 s77, s77, 0
	global_load_dwordx4 v[84:87], v49, s[76:77]
	s_sub_u32 s76, s76, 0x10000
	s_subb_u32 s77, s77, 0
	global_load_dwordx4 v[88:91], v49, s[76:77]
	s_sub_u32 s76, s76, 0x10000
	s_subb_u32 s77, s77, 0
	global_load_dwordx4 v[92:95], v49, s[76:77]
	s_sub_u32 s76, s76, 0x10000
	s_subb_u32 s77, s77, 0
	global_load_dwordx4 v[96:99], v49, s[76:77]
	s_sub_u32 s76, s76, 0x10000
	s_subb_u32 s77, s77, 0
	s_waitcnt vmcnt(11)
	v_mul_f32_e32 v0, v0, v44
	v_mul_f32_e32 v4, v4, v44
	v_mul_f32_e32 v8, v8, v44
	v_mul_f32_e32 v12, v12, v44
	v_mul_f32_e32 v16, v16, v44
	v_mul_f32_e32 v20, v20, v44
	v_mul_f32_e32 v24, v24, v44
	v_mul_f32_e32 v28, v28, v44
	v_mul_f32_e32 v32, v32, v44
	v_mul_f32_e32 v36, v36, v44
	v_mul_f32_e32 v52, v52, v44
	v_fmac_f32_e32 v0, v1, v45
	v_fmac_f32_e32 v4, v5, v45
	v_fmac_f32_e32 v8, v9, v45
	v_fmac_f32_e32 v12, v13, v45
	v_fmac_f32_e32 v16, v17, v45
	v_fmac_f32_e32 v20, v21, v45
	v_fmac_f32_e32 v24, v25, v45
	v_fmac_f32_e32 v28, v29, v45
	v_fmac_f32_e32 v32, v33, v45
	v_fmac_f32_e32 v36, v37, v45
	v_fmac_f32_e32 v52, v53, v45
	v_fmac_f32_e32 v0, v2, v46
	v_fmac_f32_e32 v4, v6, v46
	v_fmac_f32_e32 v8, v10, v46
	v_fmac_f32_e32 v12, v14, v46
	v_fmac_f32_e32 v16, v18, v46
	v_fmac_f32_e32 v20, v22, v46
	v_fmac_f32_e32 v24, v26, v46
	v_fmac_f32_e32 v28, v30, v46
	v_fmac_f32_e32 v32, v34, v46
	v_fmac_f32_e32 v36, v38, v46
	v_fmac_f32_e32 v52, v54, v46
	v_fmac_f32_e32 v0, v3, v47
	v_fmac_f32_e32 v4, v7, v47
	v_fmac_f32_e32 v8, v11, v47
	v_fmac_f32_e32 v12, v15, v47
	v_fmac_f32_e32 v16, v19, v47
	v_fmac_f32_e32 v20, v23, v47
	v_fmac_f32_e32 v24, v27, v47
	v_fmac_f32_e32 v28, v31, v47
	v_fmac_f32_e32 v32, v35, v47
	v_fmac_f32_e32 v36, v39, v47
	v_fmac_f32_e32 v52, v55, v47
	s_nop 1
	v_add_f32_dpp v0, v0, v0 quad_perm:[1,0,3,2] row_mask:0xf bank_mask:0xf
	v_add_f32_dpp v4, v4, v4 quad_perm:[1,0,3,2] row_mask:0xf bank_mask:0xf
	v_add_f32_dpp v8, v8, v8 quad_perm:[1,0,3,2] row_mask:0xf bank_mask:0xf
	v_add_f32_dpp v12, v12, v12 quad_perm:[1,0,3,2] row_mask:0xf bank_mask:0xf
	v_add_f32_dpp v16, v16, v16 quad_perm:[1,0,3,2] row_mask:0xf bank_mask:0xf
	v_add_f32_dpp v20, v20, v20 quad_perm:[1,0,3,2] row_mask:0xf bank_mask:0xf
	v_add_f32_dpp v24, v24, v24 quad_perm:[1,0,3,2] row_mask:0xf bank_mask:0xf
	v_add_f32_dpp v28, v28, v28 quad_perm:[1,0,3,2] row_mask:0xf bank_mask:0xf
	v_add_f32_dpp v32, v32, v32 quad_perm:[1,0,3,2] row_mask:0xf bank_mask:0xf
	v_add_f32_dpp v36, v36, v36 quad_perm:[1,0,3,2] row_mask:0xf bank_mask:0xf
	v_add_f32_dpp v52, v52, v52 quad_perm:[1,0,3,2] row_mask:0xf bank_mask:0xf
	s_nop 1
	v_add_f32_dpp v0, v0, v0 quad_perm:[2,3,0,1] row_mask:0xf bank_mask:0xf
	v_add_f32_dpp v4, v4, v4 quad_perm:[2,3,0,1] row_mask:0xf bank_mask:0xf
	v_add_f32_dpp v8, v8, v8 quad_perm:[2,3,0,1] row_mask:0xf bank_mask:0xf
	v_add_f32_dpp v12, v12, v12 quad_perm:[2,3,0,1] row_mask:0xf bank_mask:0xf
	v_add_f32_dpp v16, v16, v16 quad_perm:[2,3,0,1] row_mask:0xf bank_mask:0xf
	v_add_f32_dpp v20, v20, v20 quad_perm:[2,3,0,1] row_mask:0xf bank_mask:0xf
	v_add_f32_dpp v24, v24, v24 quad_perm:[2,3,0,1] row_mask:0xf bank_mask:0xf
	v_add_f32_dpp v28, v28, v28 quad_perm:[2,3,0,1] row_mask:0xf bank_mask:0xf
	v_add_f32_dpp v32, v32, v32 quad_perm:[2,3,0,1] row_mask:0xf bank_mask:0xf
	v_add_f32_dpp v36, v36, v36 quad_perm:[2,3,0,1] row_mask:0xf bank_mask:0xf
; #define LAS __attribute__((address_space(3)))
; DI float bflo(unsigned w) { return __uint_as_float(w << 16); }
; DI float bfhi(unsigned w) { return __uint_as_float(w & 0xffff0000u); }
; DI void attn_sample_unit(const Params& p, int u, const bf16_t* Q, const bf16_t* Kb, const bf16_t* Vb, bf16_t* att, LAS float* sl, int lane) {
;     ...
;     for (int e = 0; e < 9; ++e) { const int pat = e / 3, r = e - 3 * pat; const int dil = 1 << (2 * pat);
;         const int j = lane + 64 * r; const bool valid = j <= 128; const int idx = 2048 + t - dil * (valid ? j : 0);
;         float dot = 0.f;
;         if (idx >= 2048) { const bf16_t* kp = Kb + ((size_t)NP + b * 4 + (idx - 2048)) * 1024 + h * 64;
; #pragma unroll
;             for (int d8 = 0; d8 < 8; ++d8) { const u32x4 kw = *(const u32x4*)(kp + 8 * d8); const f32x4 q0 = *(const LAS f32x4*)(sl + 8 * d8), q1 = *(const LAS f32x4*)(sl + 8 * d8 + 4);
;                 dot += (bflo(kw.x) * q0[0] + bfhi(kw.x) * q0[1]) + (bflo(kw.y) * q0[2] + bfhi(kw.y) * q0[3]) + (bflo(kw.z) * q1[0] + bfhi(kw.z) * q1[1]) + (bflo(kw.w) * q1[2] + bfhi(kw.w) * q1[3]); } }
;         else { const float* kp = ck + (((size_t)b * 2048 + idx) * 16 + h) * 64;
; #pragma unroll
;             for (int d4 = 0; d4 < 16; ++d4) { const f32x4 kv = *(const f32x4*)(kp + 4 * d4); const f32x4 qv = *(const LAS f32x4*)(sl + 4 * d4); dot += (kv[0] * qv[0] + kv[1] * qv[1]) + (kv[2] * qv[2] + kv[3] * qv[3]); } }
;         if (valid) { sl[64 + pat * 192 + j] = dot; mx = fmaxf(mx, dot); } }
	v_add_f32_dpp v52, v52, v52 quad_perm:[2,3,0,1] row_mask:0xf bank_mask:0xf
	s_nop 1
	v_add_f32_dpp v0, v0, v0 row_half_mirror row_mask:0xf bank_mask:0xf
	v_add_f32_dpp v4, v4, v4 row_half_mirror row_mask:0xf bank_mask:0xf
	v_add_f32_dpp v8, v8, v8 row_half_mirror row_mask:0xf bank_mask:0xf
	v_add_f32_dpp v12, v12, v12 row_half_mirror row_mask:0xf bank_mask:0xf
	v_add_f32_dpp v16, v16, v16 row_half_mirror row_mask:0xf bank_mask:0xf
	v_add_f32_dpp v20, v20, v20 row_half_mirror row_mask:0xf bank_mask:0xf
	v_add_f32_dpp v24, v24, v24 row_half_mirror row_mask:0xf bank_mask:0xf
	v_add_f32_dpp v28, v28, v28 row_half_mirror row_mask:0xf bank_mask:0xf
	v_add_f32_dpp v32, v32, v32 row_half_mirror row_mask:0xf bank_mask:0xf
	v_add_f32_dpp v36, v36, v36 row_half_mirror row_mask:0xf bank_mask:0xf
	v_add_f32_dpp v52, v52, v52 row_half_mirror row_mask:0xf bank_mask:0xf
	s_nop 1
	v_add_f32_dpp v0, v0, v0 row_mirror row_mask:0xf bank_mask:0xf
	v_add_f32_dpp v4, v4, v4 row_mirror row_mask:0xf bank_mask:0xf
	v_add_f32_dpp v8, v8, v8 row_mirror row_mask:0xf bank_mask:0xf
	v_add_f32_dpp v12, v12, v12 row_mirror row_mask:0xf bank_mask:0xf
	v_add_f32_dpp v16, v16, v16 row_mirror row_mask:0xf bank_mask:0xf
	v_add_f32_dpp v20, v20, v20 row_mirror row_mask:0xf bank_mask:0xf
	v_add_f32_dpp v24, v24, v24 row_mirror row_mask:0xf bank_mask:0xf
	v_add_f32_dpp v28, v28, v28 row_mirror row_mask:0xf bank_mask:0xf
	v_add_f32_dpp v32, v32, v32 row_mirror row_mask:0xf bank_mask:0xf
	v_add_f32_dpp v36, v36, v36 row_mirror row_mask:0xf bank_mask:0xf
	v_add_f32_dpp v52, v52, v52 row_mirror row_mask:0xf bank_mask:0xf
	s_nop 1
	s_mov_b32 s82, 0x10001
	s_mov_b32 s83, 0x10001
	s_mov_b64 exec, s[82:83]
	ds_write_b32 v48, v0 offset:352
	v_max_f32_e32 v40, v40, v0
	ds_write_b32 v48, v4 offset:368
	v_max_f32_e32 v40, v40, v4
	ds_write_b32 v48, v8 offset:384
	v_max_f32_e32 v40, v40, v8
	ds_write_b32 v48, v12 offset:400
	v_max_f32_e32 v40, v40, v12
	ds_write_b32 v48, v16 offset:416
	v_max_f32_e32 v40, v40, v16
	ds_write_b32 v48, v20 offset:432
	v_max_f32_e32 v40, v40, v20
	ds_write_b32 v48, v24 offset:448
	v_max_f32_e32 v40, v40, v24
	ds_write_b32 v48, v28 offset:464
	v_max_f32_e32 v40, v40, v28
	ds_write_b32 v48, v32 offset:480
	v_max_f32_e32 v40, v40, v32
	ds_write_b32 v48, v36 offset:496
	v_max_f32_e32 v40, v40, v36
	s_mov_b64 exec, 1
	ds_write_b32 v48, v52 offset:512
	v_max_f32_e32 v40, v40, v52
	s_mov_b64 exec, -1
	s_nop 4
	global_load_dwordx4 v[0:3], v49, s[76:77]
	s_sub_u32 s76, s76, 0x10000
	s_subb_u32 s77, s77, 0
	global_load_dwordx4 v[4:7], v49, s[76:77]
	s_sub_u32 s76, s76, 0x10000
	s_subb_u32 s77, s77, 0
	global_load_dwordx4 v[8:11], v49, s[76:77]
	s_sub_u32 s76, s76, 0x10000
	s_subb_u32 s77, s77, 0
	global_load_dwordx4 v[12:15], v49, s[76:77]
	s_sub_u32 s76, s76, 0x10000
	s_subb_u32 s77, s77, 0
	global_load_dwordx4 v[16:19], v49, s[76:77]
	s_sub_u32 s76, s76, 0x10000
	s_subb_u32 s77, s77, 0
	global_load_dwordx4 v[20:23], v49, s[76:77]
	s_sub_u32 s76, s76, 0x10000
	s_subb_u32 s77, s77, 0
	global_load_dwordx4 v[24:27], v49, s[76:77]
	s_sub_u32 s76, s76, 0x10000
	s_subb_u32 s77, s77, 0
	global_load_dwordx4 v[28:31], v49, s[76:77]
	s_sub_u32 s76, s76, 0x10000
	s_subb_u32 s77, s77, 0
	global_load_dwordx4 v[32:35], v49, s[76:77]
	s_sub_u32 s76, s76, 0x10000
	s_subb_u32 s77, s77, 0
	global_load_dwordx4 v[36:39], v49, s[76:77]
	s_sub_u32 s76, s76, 0x10000
	s_subb_u32 s77, s77, 0
	global_load_dwordx4 v[52:55], v49, s[76:77]
	s_sub_u32 s76, s76, 0x10000
	s_subb_u32 s77, s77, 0
	s_waitcnt vmcnt(11)
	v_mul_f32_e32 v56, v56, v44
	v_mul_f32_e32 v60, v60, v44
	v_mul_f32_e32 v64, v64, v44
	v_mul_f32_e32 v68, v68, v44
	v_mul_f32_e32 v72, v72, v44
	v_mul_f32_e32 v76, v76, v44
	v_mul_f32_e32 v80, v80, v44
	v_mul_f32_e32 v84, v84, v44
	v_mul_f32_e32 v88, v88, v44
	v_mul_f32_e32 v92, v92, v44
	v_mul_f32_e32 v96, v96, v44
	v_fmac_f32_e32 v56, v57, v45
	v_fmac_f32_e32 v60, v61, v45
	v_fmac_f32_e32 v64, v65, v45
	v_fmac_f32_e32 v68, v69, v45
	v_fmac_f32_e32 v72, v73, v45
	v_fmac_f32_e32 v76, v77, v45
	v_fmac_f32_e32 v80, v81, v45
	v_fmac_f32_e32 v84, v85, v45
	v_fmac_f32_e32 v88, v89, v45
	v_fmac_f32_e32 v92, v93, v45
	v_fmac_f32_e32 v96, v97, v45
	v_fmac_f32_e32 v56, v58, v46
	v_fmac_f32_e32 v60, v62, v46
	v_fmac_f32_e32 v64, v66, v46
	v_fmac_f32_e32 v68, v70, v46
	v_fmac_f32_e32 v72, v74, v46
	v_fmac_f32_e32 v76, v78, v46
	v_fmac_f32_e32 v80, v82, v46
	v_fmac_f32_e32 v84, v86, v46
	v_fmac_f32_e32 v88, v90, v46
	v_fmac_f32_e32 v92, v94, v46
	v_fmac_f32_e32 v96, v98, v46
	v_fmac_f32_e32 v56, v59, v47
	v_fmac_f32_e32 v60, v63, v47
	v_fmac_f32_e32 v64, v67, v47
	v_fmac_f32_e32 v68, v71, v47
	v_fmac_f32_e32 v72, v75, v47
	v_fmac_f32_e32 v76, v79, v47
	v_fmac_f32_e32 v80, v83, v47
	v_fmac_f32_e32 v84, v87, v47
	v_fmac_f32_e32 v88, v91, v47
	v_fmac_f32_e32 v92, v95, v47
	v_fmac_f32_e32 v96, v99, v47
	s_nop 1
	v_add_f32_dpp v56, v56, v56 quad_perm:[1,0,3,2] row_mask:0xf bank_mask:0xf
	v_add_f32_dpp v60, v60, v60 quad_perm:[1,0,3,2] row_mask:0xf bank_mask:0xf
	v_add_f32_dpp v64, v64, v64 quad_perm:[1,0,3,2] row_mask:0xf bank_mask:0xf
	v_add_f32_dpp v68, v68, v68 quad_perm:[1,0,3,2] row_mask:0xf bank_mask:0xf
	v_add_f32_dpp v72, v72, v72 quad_perm:[1,0,3,2] row_mask:0xf bank_mask:0xf
	v_add_f32_dpp v76, v76, v76 quad_perm:[1,0,3,2] row_mask:0xf bank_mask:0xf
	v_add_f32_dpp v80, v80, v80 quad_perm:[1,0,3,2] row_mask:0xf bank_mask:0xf
	v_add_f32_dpp v84, v84, v84 quad_perm:[1,0,3,2] row_mask:0xf bank_mask:0xf
	v_add_f32_dpp v88, v88, v88 quad_perm:[1,0,3,2] row_mask:0xf bank_mask:0xf
	v_add_f32_dpp v92, v92, v92 quad_perm:[1,0,3,2] row_mask:0xf bank_mask:0xf
	v_add_f32_dpp v96, v96, v96 quad_perm:[1,0,3,2] row_mask:0xf bank_mask:0xf
; #define LAS __attribute__((address_space(3)))
; DI float bflo(unsigned w) { return __uint_as_float(w << 16); }
; DI float bfhi(unsigned w) { return __uint_as_float(w & 0xffff0000u); }
; DI void attn_sample_unit(const Params& p, int u, const bf16_t* Q, const bf16_t* Kb, const bf16_t* Vb, bf16_t* att, LAS float* sl, int lane) {
;     ...
;     for (int e = 0; e < 9; ++e) { const int pat = e / 3, r = e - 3 * pat; const int dil = 1 << (2 * pat);
;         const int j = lane + 64 * r; const bool valid = j <= 128; const int idx = 2048 + t - dil * (valid ? j : 0);
;         float dot = 0.f;
;         if (idx >= 2048) { const bf16_t* kp = Kb + ((size_t)NP + b * 4 + (idx - 2048)) * 1024 + h * 64;
; #pragma unroll
;             for (int d8 = 0; d8 < 8; ++d8) { const u32x4 kw = *(const u32x4*)(kp + 8 * d8); const f32x4 q0 = *(const LAS f32x4*)(sl + 8 * d8), q1 = *(const LAS f32x4*)(sl + 8 * d8 + 4);
;                 dot += (bflo(kw.x) * q0[0] + bfhi(kw.x) * q0[1]) + (bflo(kw.y) * q0[2] + bfhi(kw.y) * q0[3]) + (bflo(kw.z) * q1[0] + bfhi(kw.z) * q1[1]) + (bflo(kw.w) * q1[2] + bfhi(kw.w) * q1[3]); } }
;         else { const float* kp = ck + (((size_t)b * 2048 + idx) * 16 + h) * 64;
; #pragma unroll
;             for (int d4 = 0; d4 < 16; ++d4) { const f32x4 kv = *(const f32x4*)(kp + 4 * d4); const f32x4 qv = *(const LAS f32x4*)(sl + 4 * d4); dot += (kv[0] * qv[0] + kv[1] * qv[1]) + (kv[2] * qv[2] + kv[3] * qv[3]); } }
;         if (valid) { sl[64 + pat * 192 + j] = dot; mx = fmaxf(mx, dot); } }
	s_nop 1
	v_add_f32_dpp v56, v56, v56 quad_perm:[2,3,0,1] row_mask:0xf bank_mask:0xf
	v_add_f32_dpp v60, v60, v60 quad_perm:[2,3,0,1] row_mask:0xf bank_mask:0xf
	v_add_f32_dpp v64, v64, v64 quad_perm:[2,3,0,1] row_mask:0xf bank_mask:0xf
	v_add_f32_dpp v68, v68, v68 quad_perm:[2,3,0,1] row_mask:0xf bank_mask:0xf
	v_add_f32_dpp v72, v72, v72 quad_perm:[2,3,0,1] row_mask:0xf bank_mask:0xf
	v_add_f32_dpp v76, v76, v76 quad_perm:[2,3,0,1] row_mask:0xf bank_mask:0xf
	v_add_f32_dpp v80, v80, v80 quad_perm:[2,3,0,1] row_mask:0xf bank_mask:0xf
	v_add_f32_dpp v84, v84, v84 quad_perm:[2,3,0,1] row_mask:0xf bank_mask:0xf
	v_add_f32_dpp v88, v88, v88 quad_perm:[2,3,0,1] row_mask:0xf bank_mask:0xf
	v_add_f32_dpp v92, v92, v92 quad_perm:[2,3,0,1] row_mask:0xf bank_mask:0xf
	v_add_f32_dpp v96, v96, v96 quad_perm:[2,3,0,1] row_mask:0xf bank_mask:0xf
	s_nop 1
	v_add_f32_dpp v56, v56, v56 row_half_mirror row_mask:0xf bank_mask:0xf
	v_add_f32_dpp v60, v60, v60 row_half_mirror row_mask:0xf bank_mask:0xf
	v_add_f32_dpp v64, v64, v64 row_half_mirror row_mask:0xf bank_mask:0xf
	v_add_f32_dpp v68, v68, v68 row_half_mirror row_mask:0xf bank_mask:0xf
	v_add_f32_dpp v72, v72, v72 row_half_mirror row_mask:0xf bank_mask:0xf
	v_add_f32_dpp v76, v76, v76 row_half_mirror row_mask:0xf bank_mask:0xf
	v_add_f32_dpp v80, v80, v80 row_half_mirror row_mask:0xf bank_mask:0xf
	v_add_f32_dpp v84, v84, v84 row_half_mirror row_mask:0xf bank_mask:0xf
	v_add_f32_dpp v88, v88, v88 row_half_mirror row_mask:0xf bank_mask:0xf
	v_add_f32_dpp v92, v92, v92 row_half_mirror row_mask:0xf bank_mask:0xf
	v_add_f32_dpp v96, v96, v96 row_half_mirror row_mask:0xf bank_mask:0xf
	s_nop 1
	v_add_f32_dpp v56, v56, v56 row_mirror row_mask:0xf bank_mask:0xf
	v_add_f32_dpp v60, v60, v60 row_mirror row_mask:0xf bank_mask:0xf
	v_add_f32_dpp v64, v64, v64 row_mirror row_mask:0xf bank_mask:0xf
	v_add_f32_dpp v68, v68, v68 row_mirror row_mask:0xf bank_mask:0xf
	v_add_f32_dpp v72, v72, v72 row_mirror row_mask:0xf bank_mask:0xf
	v_add_f32_dpp v76, v76, v76 row_mirror row_mask:0xf bank_mask:0xf
	v_add_f32_dpp v80, v80, v80 row_mirror row_mask:0xf bank_mask:0xf
	v_add_f32_dpp v84, v84, v84 row_mirror row_mask:0xf bank_mask:0xf
	v_add_f32_dpp v88, v88, v88 row_mirror row_mask:0xf bank_mask:0xf
	v_add_f32_dpp v92, v92, v92 row_mirror row_mask:0xf bank_mask:0xf
	v_add_f32_dpp v96, v96, v96 row_mirror row_mask:0xf bank_mask:0xf
	s_nop 1
	s_mov_b32 s82, 0x10000
	s_mov_b32 s83, 0x10001
	s_mov_b64 exec, s[82:83]
	ds_write_b32 v48, v56 offset:768
	v_max_f32_e32 v40, v40, v56
	s_mov_b32 s82, 0x10001
	s_mov_b32 s83, 0x10001
	s_mov_b64 exec, s[82:83]
	ds_write_b32 v48, v60 offset:784
	v_max_f32_e32 v40, v40, v60
	ds_write_b32 v48, v64 offset:800
	v_max_f32_e32 v40, v40, v64
	ds_write_b32 v48, v68 offset:816
	v_max_f32_e32 v40, v40, v68
	ds_write_b32 v48, v72 offset:832
	v_max_f32_e32 v40, v40, v72
	ds_write_b32 v48, v76 offset:848
	v_max_f32_e32 v40, v40, v76
	ds_write_b32 v48, v80 offset:864
	v_max_f32_e32 v40, v40, v80
	ds_write_b32 v48, v84 offset:880
	v_max_f32_e32 v40, v40, v84
	ds_write_b32 v48, v88 offset:896
	v_max_f32_e32 v40, v40, v88
	ds_write_b32 v48, v92 offset:912
	v_max_f32_e32 v40, v40, v92
	ds_write_b32 v48, v96 offset:928
	v_max_f32_e32 v40, v40, v96
	s_mov_b64 exec, -1
	s_nop 4
	global_load_dwordx4 v[56:59], v49, s[76:77]
	s_sub_u32 s76, s76, 0x10000
	s_subb_u32 s77, s77, 0
	global_load_dwordx4 v[60:63], v49, s[76:77]
	s_sub_u32 s76, s76, 0x10000
	s_subb_u32 s77, s77, 0
	global_load_dwordx4 v[64:67], v49, s[76:77]
	s_sub_u32 s76, s76, 0x10000
	s_subb_u32 s77, s77, 0
	global_load_dwordx4 v[68:71], v49, s[76:77]
	s_sub_u32 s76, s76, 0x10000
	s_subb_u32 s77, s77, 0
	global_load_dwordx4 v[72:75], v49, s[76:77]
	s_sub_u32 s76, s76, 0x10000
	s_subb_u32 s77, s77, 0
	global_load_dwordx4 v[76:79], v49, s[76:77]
	s_sub_u32 s76, s76, 0x10000
	s_subb_u32 s77, s77, 0
	global_load_dwordx4 v[80:83], v49, s[76:77]
	s_sub_u32 s76, s76, 0x10000
	s_subb_u32 s77, s77, 0
	global_load_dwordx4 v[84:87], v49, s[76:77]
	s_sub_u32 s76, s76, 0x10000
	s_subb_u32 s77, s77, 0
	global_load_dwordx4 v[88:91], v49, s[76:77]
	s_sub_u32 s76, s76, 0x10000
	s_subb_u32 s77, s77, 0
	global_load_dwordx4 v[92:95], v49, s[76:77]
	s_sub_u32 s76, s76, 0x10000
	s_subb_u32 s77, s77, 0
	s_mov_b64 exec, 0xffff
	global_load_dwordx4 v[96:99], v49, s[76:77]
	s_mov_b64 exec, -1
	s_waitcnt vmcnt(11)
; #define LAS __attribute__((address_space(3)))
; DI float bflo(unsigned w) { return __uint_as_float(w << 16); }
; DI float bfhi(unsigned w) { return __uint_as_float(w & 0xffff0000u); }
; DI void attn_sample_unit(const Params& p, int u, const bf16_t* Q, const bf16_t* Kb, const bf16_t* Vb, bf16_t* att, LAS float* sl, int lane) {
;     ...
;     for (int e = 0; e < 9; ++e) { const int pat = e / 3, r = e - 3 * pat; const int dil = 1 << (2 * pat);
;         const int j = lane + 64 * r; const bool valid = j <= 128; const int idx = 2048 + t - dil * (valid ? j : 0);
;         float dot = 0.f;
;         if (idx >= 2048) { const bf16_t* kp = Kb + ((size_t)NP + b * 4 + (idx - 2048)) * 1024 + h * 64;
; #pragma unroll
;             for (int d8 = 0; d8 < 8; ++d8) { const u32x4 kw = *(const u32x4*)(kp + 8 * d8); const f32x4 q0 = *(const LAS f32x4*)(sl + 8 * d8), q1 = *(const LAS f32x4*)(sl + 8 * d8 + 4);
;                 dot += (bflo(kw.x) * q0[0] + bfhi(kw.x) * q0[1]) + (bflo(kw.y) * q0[2] + bfhi(kw.y) * q0[3]) + (bflo(kw.z) * q1[0] + bfhi(kw.z) * q1[1]) + (bflo(kw.w) * q1[2] + bfhi(kw.w) * q1[3]); } }
;         else { const float* kp = ck + (((size_t)b * 2048 + idx) * 16 + h) * 64;
; #pragma unroll
;             for (int d4 = 0; d4 < 16; ++d4) { const f32x4 kv = *(const f32x4*)(kp + 4 * d4); const f32x4 qv = *(const LAS f32x4*)(sl + 4 * d4); dot += (kv[0] * qv[0] + kv[1] * qv[1]) + (kv[2] * qv[2] + kv[3] * qv[3]); } }
;         if (valid) { sl[64 + pat * 192 + j] = dot; mx = fmaxf(mx, dot); } }
	v_mul_f32_e32 v0, v0, v44
	v_mul_f32_e32 v4, v4, v44
	v_mul_f32_e32 v8, v8, v44
	v_mul_f32_e32 v12, v12, v44
	v_mul_f32_e32 v16, v16, v44
	v_mul_f32_e32 v20, v20, v44
	v_mul_f32_e32 v24, v24, v44
	v_mul_f32_e32 v28, v28, v44
	v_mul_f32_e32 v32, v32, v44
	v_mul_f32_e32 v36, v36, v44
	v_mul_f32_e32 v52, v52, v44
	v_fmac_f32_e32 v0, v1, v45
	v_fmac_f32_e32 v4, v5, v45
	v_fmac_f32_e32 v8, v9, v45
	v_fmac_f32_e32 v12, v13, v45
	v_fmac_f32_e32 v16, v17, v45
	v_fmac_f32_e32 v20, v21, v45
	v_fmac_f32_e32 v24, v25, v45
	v_fmac_f32_e32 v28, v29, v45
	v_fmac_f32_e32 v32, v33, v45
	v_fmac_f32_e32 v36, v37, v45
	v_fmac_f32_e32 v52, v53, v45
	v_fmac_f32_e32 v0, v2, v46
	v_fmac_f32_e32 v4, v6, v46
	v_fmac_f32_e32 v8, v10, v46
	v_fmac_f32_e32 v12, v14, v46
	v_fmac_f32_e32 v16, v18, v46
	v_fmac_f32_e32 v20, v22, v46
	v_fmac_f32_e32 v24, v26, v46
	v_fmac_f32_e32 v28, v30, v46
	v_fmac_f32_e32 v32, v34, v46
	v_fmac_f32_e32 v36, v38, v46
	v_fmac_f32_e32 v52, v54, v46
	v_fmac_f32_e32 v0, v3, v47
	v_fmac_f32_e32 v4, v7, v47
	v_fmac_f32_e32 v8, v11, v47
	v_fmac_f32_e32 v12, v15, v47
	v_fmac_f32_e32 v16, v19, v47
	v_fmac_f32_e32 v20, v23, v47
	v_fmac_f32_e32 v24, v27, v47
	v_fmac_f32_e32 v28, v31, v47
	v_fmac_f32_e32 v32, v35, v47
	v_fmac_f32_e32 v36, v39, v47
	v_fmac_f32_e32 v52, v55, v47
	s_nop 1
	v_add_f32_dpp v0, v0, v0 quad_perm:[1,0,3,2] row_mask:0xf bank_mask:0xf
	v_add_f32_dpp v4, v4, v4 quad_perm:[1,0,3,2] row_mask:0xf bank_mask:0xf
	v_add_f32_dpp v8, v8, v8 quad_perm:[1,0,3,2] row_mask:0xf bank_mask:0xf
	v_add_f32_dpp v12, v12, v12 quad_perm:[1,0,3,2] row_mask:0xf bank_mask:0xf
	v_add_f32_dpp v16, v16, v16 quad_perm:[1,0,3,2] row_mask:0xf bank_mask:0xf
	v_add_f32_dpp v20, v20, v20 quad_perm:[1,0,3,2] row_mask:0xf bank_mask:0xf
	v_add_f32_dpp v24, v24, v24 quad_perm:[1,0,3,2] row_mask:0xf bank_mask:0xf
	v_add_f32_dpp v28, v28, v28 quad_perm:[1,0,3,2] row_mask:0xf bank_mask:0xf
	v_add_f32_dpp v32, v32, v32 quad_perm:[1,0,3,2] row_mask:0xf bank_mask:0xf
	v_add_f32_dpp v36, v36, v36 quad_perm:[1,0,3,2] row_mask:0xf bank_mask:0xf
	v_add_f32_dpp v52, v52, v52 quad_perm:[1,0,3,2] row_mask:0xf bank_mask:0xf
	s_nop 1
	v_add_f32_dpp v0, v0, v0 quad_perm:[2,3,0,1] row_mask:0xf bank_mask:0xf
	v_add_f32_dpp v4, v4, v4 quad_perm:[2,3,0,1] row_mask:0xf bank_mask:0xf
	v_add_f32_dpp v8, v8, v8 quad_perm:[2,3,0,1] row_mask:0xf bank_mask:0xf
	v_add_f32_dpp v12, v12, v12 quad_perm:[2,3,0,1] row_mask:0xf bank_mask:0xf
	v_add_f32_dpp v16, v16, v16 quad_perm:[2,3,0,1] row_mask:0xf bank_mask:0xf
	v_add_f32_dpp v20, v20, v20 quad_perm:[2,3,0,1] row_mask:0xf bank_mask:0xf
	v_add_f32_dpp v24, v24, v24 quad_perm:[2,3,0,1] row_mask:0xf bank_mask:0xf
	v_add_f32_dpp v28, v28, v28 quad_perm:[2,3,0,1] row_mask:0xf bank_mask:0xf
	v_add_f32_dpp v32, v32, v32 quad_perm:[2,3,0,1] row_mask:0xf bank_mask:0xf
	v_add_f32_dpp v36, v36, v36 quad_perm:[2,3,0,1] row_mask:0xf bank_mask:0xf
	v_add_f32_dpp v52, v52, v52 quad_perm:[2,3,0,1] row_mask:0xf bank_mask:0xf
	s_nop 1
	v_add_f32_dpp v0, v0, v0 row_half_mirror row_mask:0xf bank_mask:0xf
	v_add_f32_dpp v4, v4, v4 row_half_mirror row_mask:0xf bank_mask:0xf
	v_add_f32_dpp v8, v8, v8 row_half_mirror row_mask:0xf bank_mask:0xf
	v_add_f32_dpp v12, v12, v12 row_half_mirror row_mask:0xf bank_mask:0xf
	v_add_f32_dpp v16, v16, v16 row_half_mirror row_mask:0xf bank_mask:0xf
	v_add_f32_dpp v20, v20, v20 row_half_mirror row_mask:0xf bank_mask:0xf
	v_add_f32_dpp v24, v24, v24 row_half_mirror row_mask:0xf bank_mask:0xf
	v_add_f32_dpp v28, v28, v28 row_half_mirror row_mask:0xf bank_mask:0xf
	v_add_f32_dpp v32, v32, v32 row_half_mirror row_mask:0xf bank_mask:0xf
	v_add_f32_dpp v36, v36, v36 row_half_mirror row_mask:0xf bank_mask:0xf
	v_add_f32_dpp v52, v52, v52 row_half_mirror row_mask:0xf bank_mask:0xf
	s_nop 1
	v_add_f32_dpp v0, v0, v0 row_mirror row_mask:0xf bank_mask:0xf
	v_add_f32_dpp v4, v4, v4 row_mirror row_mask:0xf bank_mask:0xf
	v_add_f32_dpp v8, v8, v8 row_mirror row_mask:0xf bank_mask:0xf
	v_add_f32_dpp v12, v12, v12 row_mirror row_mask:0xf bank_mask:0xf
	v_add_f32_dpp v16, v16, v16 row_mirror row_mask:0xf bank_mask:0xf
	v_add_f32_dpp v20, v20, v20 row_mirror row_mask:0xf bank_mask:0xf
	v_add_f32_dpp v24, v24, v24 row_mirror row_mask:0xf bank_mask:0xf
	v_add_f32_dpp v28, v28, v28 row_mirror row_mask:0xf bank_mask:0xf
	v_add_f32_dpp v32, v32, v32 row_mirror row_mask:0xf bank_mask:0xf
	v_add_f32_dpp v36, v36, v36 row_mirror row_mask:0xf bank_mask:0xf
	v_add_f32_dpp v52, v52, v52 row_mirror row_mask:0xf bank_mask:0xf
	s_nop 1
	s_mov_b32 s82, 0x10001
	s_mov_b32 s83, 0x10001
	s_mov_b64 exec, s[82:83]
	ds_write_b32 v48, v0 offset:944
	v_max_f32_e32 v40, v40, v0
	ds_write_b32 v48, v4 offset:960
	v_max_f32_e32 v40, v40, v4
	ds_write_b32 v48, v8 offset:976
	v_max_f32_e32 v40, v40, v8
	ds_write_b32 v48, v12 offset:992
	v_max_f32_e32 v40, v40, v12
	ds_write_b32 v48, v16 offset:1008
	v_max_f32_e32 v40, v40, v16
	ds_write_b32 v48, v20 offset:1024
	v_max_f32_e32 v40, v40, v20
	ds_write_b32 v48, v24 offset:1040
	v_max_f32_e32 v40, v40, v24
	ds_write_b32 v48, v28 offset:1056
	v_max_f32_e32 v40, v40, v28
	ds_write_b32 v48, v32 offset:1072
	v_max_f32_e32 v40, v40, v32
	ds_write_b32 v48, v36 offset:1088
	v_max_f32_e32 v40, v40, v36
	ds_write_b32 v48, v52 offset:1104
	v_max_f32_e32 v40, v40, v52
	s_mov_b64 exec, -1
	s_nop 4
	v_lshlrev_b32_e32 v49, 4, v41
	v_sub_u32_e32 v49, s2, v49
	v_min_i32_e32 v50, 0x7ff, v49
	v_lshl_add_u32 v49, v49, 12, v43
	v_lshl_add_u32 v50, v50, 12, v43
	s_mov_b64 s[76:77], s[84:85]
	global_load_dwordx4 v[0:3], v50, s[76:77]
	s_sub_u32 s76, s76, 0x40000
	s_subb_u32 s77, s77, 0
	global_load_dwordx4 v[4:7], v49, s[76:77]
	s_sub_u32 s76, s76, 0x40000
	s_subb_u32 s77, s77, 0
	global_load_dwordx4 v[8:11], v49, s[76:77]
	s_sub_u32 s76, s76, 0x40000
	s_subb_u32 s77, s77, 0
	global_load_dwordx4 v[12:15], v49, s[76:77]
	s_sub_u32 s76, s76, 0x40000
	s_subb_u32 s77, s77, 0
	global_load_dwordx4 v[16:19], v49, s[76:77]
	s_sub_u32 s76, s76, 0x40000
	s_subb_u32 s77, s77, 0
	global_load_dwordx4 v[20:23], v49, s[76:77]
	s_sub_u32 s76, s76, 0x40000
	s_subb_u32 s77, s77, 0
	global_load_dwordx4 v[24:27], v49, s[76:77]
	s_sub_u32 s76, s76, 0x40000
	s_subb_u32 s77, s77, 0
	global_load_dwordx4 v[28:31], v49, s[76:77]
	s_sub_u32 s76, s76, 0x40000
	s_subb_u32 s77, s77, 0
	global_load_dwordx4 v[32:35], v49, s[76:77]
	s_sub_u32 s76, s76, 0x40000
	s_subb_u32 s77, s77, 0
	global_load_dwordx4 v[36:39], v49, s[76:77]
	s_sub_u32 s76, s76, 0x40000
	s_subb_u32 s77, s77, 0
	global_load_dwordx4 v[52:55], v49, s[76:77]
	s_sub_u32 s76, s76, 0x40000
	s_subb_u32 s77, s77, 0
	s_waitcnt vmcnt(11)
; #define LAS __attribute__((address_space(3)))
; DI float bflo(unsigned w) { return __uint_as_float(w << 16); }
; DI float bfhi(unsigned w) { return __uint_as_float(w & 0xffff0000u); }
; DI void attn_sample_unit(const Params& p, int u, const bf16_t* Q, const bf16_t* Kb, const bf16_t* Vb, bf16_t* att, LAS float* sl, int lane) {
;     ...
;     for (int e = 0; e < 9; ++e) { const int pat = e / 3, r = e - 3 * pat; const int dil = 1 << (2 * pat);
;         const int j = lane + 64 * r; const bool valid = j <= 128; const int idx = 2048 + t - dil * (valid ? j : 0);
;         float dot = 0.f;
;         if (idx >= 2048) { const bf16_t* kp = Kb + ((size_t)NP + b * 4 + (idx - 2048)) * 1024 + h * 64;
; #pragma unroll
;             for (int d8 = 0; d8 < 8; ++d8) { const u32x4 kw = *(const u32x4*)(kp + 8 * d8); const f32x4 q0 = *(const LAS f32x4*)(sl + 8 * d8), q1 = *(const LAS f32x4*)(sl + 8 * d8 + 4);
;                 dot += (bflo(kw.x) * q0[0] + bfhi(kw.x) * q0[1]) + (bflo(kw.y) * q0[2] + bfhi(kw.y) * q0[3]) + (bflo(kw.z) * q1[0] + bfhi(kw.z) * q1[1]) + (bflo(kw.w) * q1[2] + bfhi(kw.w) * q1[3]); } }
;         else { const float* kp = ck + (((size_t)b * 2048 + idx) * 16 + h) * 64;
; #pragma unroll
;             for (int d4 = 0; d4 < 16; ++d4) { const f32x4 kv = *(const f32x4*)(kp + 4 * d4); const f32x4 qv = *(const LAS f32x4*)(sl + 4 * d4); dot += (kv[0] * qv[0] + kv[1] * qv[1]) + (kv[2] * qv[2] + kv[3] * qv[3]); } }
;         if (valid) { sl[64 + pat * 192 + j] = dot; mx = fmaxf(mx, dot); } }
	v_mul_f32_e32 v56, v56, v44
	v_mul_f32_e32 v60, v60, v44
	v_mul_f32_e32 v64, v64, v44
	v_mul_f32_e32 v68, v68, v44
	v_mul_f32_e32 v72, v72, v44
	v_mul_f32_e32 v76, v76, v44
	v_mul_f32_e32 v80, v80, v44
	v_mul_f32_e32 v84, v84, v44
	v_mul_f32_e32 v88, v88, v44
	v_mul_f32_e32 v92, v92, v44
	v_mul_f32_e32 v96, v96, v44
	v_fmac_f32_e32 v56, v57, v45
	v_fmac_f32_e32 v60, v61, v45
	v_fmac_f32_e32 v64, v65, v45
	v_fmac_f32_e32 v68, v69, v45
	v_fmac_f32_e32 v72, v73, v45
	v_fmac_f32_e32 v76, v77, v45
	v_fmac_f32_e32 v80, v81, v45
	v_fmac_f32_e32 v84, v85, v45
	v_fmac_f32_e32 v88, v89, v45
	v_fmac_f32_e32 v92, v93, v45
	v_fmac_f32_e32 v96, v97, v45
	v_fmac_f32_e32 v56, v58, v46
	v_fmac_f32_e32 v60, v62, v46
	v_fmac_f32_e32 v64, v66, v46
	v_fmac_f32_e32 v68, v70, v46
	v_fmac_f32_e32 v72, v74, v46
	v_fmac_f32_e32 v76, v78, v46
	v_fmac_f32_e32 v80, v82, v46
	v_fmac_f32_e32 v84, v86, v46
	v_fmac_f32_e32 v88, v90, v46
	v_fmac_f32_e32 v92, v94, v46
	v_fmac_f32_e32 v96, v98, v46
	v_fmac_f32_e32 v56, v59, v47
	v_fmac_f32_e32 v60, v63, v47
	v_fmac_f32_e32 v64, v67, v47
	v_fmac_f32_e32 v68, v71, v47
	v_fmac_f32_e32 v72, v75, v47
	v_fmac_f32_e32 v76, v79, v47
	v_fmac_f32_e32 v80, v83, v47
	v_fmac_f32_e32 v84, v87, v47
	v_fmac_f32_e32 v88, v91, v47
	v_fmac_f32_e32 v92, v95, v47
	v_fmac_f32_e32 v96, v99, v47
	s_nop 1
	v_add_f32_dpp v56, v56, v56 quad_perm:[1,0,3,2] row_mask:0xf bank_mask:0xf
	v_add_f32_dpp v60, v60, v60 quad_perm:[1,0,3,2] row_mask:0xf bank_mask:0xf
	v_add_f32_dpp v64, v64, v64 quad_perm:[1,0,3,2] row_mask:0xf bank_mask:0xf
	v_add_f32_dpp v68, v68, v68 quad_perm:[1,0,3,2] row_mask:0xf bank_mask:0xf
	v_add_f32_dpp v72, v72, v72 quad_perm:[1,0,3,2] row_mask:0xf bank_mask:0xf
	v_add_f32_dpp v76, v76, v76 quad_perm:[1,0,3,2] row_mask:0xf bank_mask:0xf
	v_add_f32_dpp v80, v80, v80 quad_perm:[1,0,3,2] row_mask:0xf bank_mask:0xf
	v_add_f32_dpp v84, v84, v84 quad_perm:[1,0,3,2] row_mask:0xf bank_mask:0xf
	v_add_f32_dpp v88, v88, v88 quad_perm:[1,0,3,2] row_mask:0xf bank_mask:0xf
	v_add_f32_dpp v92, v92, v92 quad_perm:[1,0,3,2] row_mask:0xf bank_mask:0xf
	v_add_f32_dpp v96, v96, v96 quad_perm:[1,0,3,2] row_mask:0xf bank_mask:0xf
	s_nop 1
	v_add_f32_dpp v56, v56, v56 quad_perm:[2,3,0,1] row_mask:0xf bank_mask:0xf
	v_add_f32_dpp v60, v60, v60 quad_perm:[2,3,0,1] row_mask:0xf bank_mask:0xf
	v_add_f32_dpp v64, v64, v64 quad_perm:[2,3,0,1] row_mask:0xf bank_mask:0xf
	v_add_f32_dpp v68, v68, v68 quad_perm:[2,3,0,1] row_mask:0xf bank_mask:0xf
	v_add_f32_dpp v72, v72, v72 quad_perm:[2,3,0,1] row_mask:0xf bank_mask:0xf
	v_add_f32_dpp v76, v76, v76 quad_perm:[2,3,0,1] row_mask:0xf bank_mask:0xf
	v_add_f32_dpp v80, v80, v80 quad_perm:[2,3,0,1] row_mask:0xf bank_mask:0xf
	v_add_f32_dpp v84, v84, v84 quad_perm:[2,3,0,1] row_mask:0xf bank_mask:0xf
	v_add_f32_dpp v88, v88, v88 quad_perm:[2,3,0,1] row_mask:0xf bank_mask:0xf
	v_add_f32_dpp v92, v92, v92 quad_perm:[2,3,0,1] row_mask:0xf bank_mask:0xf
	v_add_f32_dpp v96, v96, v96 quad_perm:[2,3,0,1] row_mask:0xf bank_mask:0xf
	s_nop 1
	v_add_f32_dpp v56, v56, v56 row_half_mirror row_mask:0xf bank_mask:0xf
	v_add_f32_dpp v60, v60, v60 row_half_mirror row_mask:0xf bank_mask:0xf
	v_add_f32_dpp v64, v64, v64 row_half_mirror row_mask:0xf bank_mask:0xf
	v_add_f32_dpp v68, v68, v68 row_half_mirror row_mask:0xf bank_mask:0xf
	v_add_f32_dpp v72, v72, v72 row_half_mirror row_mask:0xf bank_mask:0xf
	v_add_f32_dpp v76, v76, v76 row_half_mirror row_mask:0xf bank_mask:0xf
	v_add_f32_dpp v80, v80, v80 row_half_mirror row_mask:0xf bank_mask:0xf
	v_add_f32_dpp v84, v84, v84 row_half_mirror row_mask:0xf bank_mask:0xf
	v_add_f32_dpp v88, v88, v88 row_half_mirror row_mask:0xf bank_mask:0xf
	v_add_f32_dpp v92, v92, v92 row_half_mirror row_mask:0xf bank_mask:0xf
	v_add_f32_dpp v96, v96, v96 row_half_mirror row_mask:0xf bank_mask:0xf
	s_nop 1
	v_add_f32_dpp v56, v56, v56 row_mirror row_mask:0xf bank_mask:0xf
	v_add_f32_dpp v60, v60, v60 row_mirror row_mask:0xf bank_mask:0xf
	v_add_f32_dpp v64, v64, v64 row_mirror row_mask:0xf bank_mask:0xf
	v_add_f32_dpp v68, v68, v68 row_mirror row_mask:0xf bank_mask:0xf
	v_add_f32_dpp v72, v72, v72 row_mirror row_mask:0xf bank_mask:0xf
	v_add_f32_dpp v76, v76, v76 row_mirror row_mask:0xf bank_mask:0xf
	v_add_f32_dpp v80, v80, v80 row_mirror row_mask:0xf bank_mask:0xf
	v_add_f32_dpp v84, v84, v84 row_mirror row_mask:0xf bank_mask:0xf
	v_add_f32_dpp v88, v88, v88 row_mirror row_mask:0xf bank_mask:0xf
	v_add_f32_dpp v92, v92, v92 row_mirror row_mask:0xf bank_mask:0xf
	v_add_f32_dpp v96, v96, v96 row_mirror row_mask:0xf bank_mask:0xf
	s_nop 1
	s_mov_b32 s82, 0x10001
	s_mov_b32 s83, 0x10001
	s_mov_b64 exec, s[82:83]
	ds_write_b32 v48, v56 offset:1120
	v_max_f32_e32 v40, v40, v56
	ds_write_b32 v48, v60 offset:1136
	v_max_f32_e32 v40, v40, v60
	ds_write_b32 v48, v64 offset:1152
	v_max_f32_e32 v40, v40, v64
	ds_write_b32 v48, v68 offset:1168
	v_max_f32_e32 v40, v40, v68
	ds_write_b32 v48, v72 offset:1184
	v_max_f32_e32 v40, v40, v72
	ds_write_b32 v48, v76 offset:1200
	v_max_f32_e32 v40, v40, v76
	ds_write_b32 v48, v80 offset:1216
	v_max_f32_e32 v40, v40, v80
	ds_write_b32 v48, v84 offset:1232
	v_max_f32_e32 v40, v40, v84
	ds_write_b32 v48, v88 offset:1248
	v_max_f32_e32 v40, v40, v88
	ds_write_b32 v48, v92 offset:1264
	v_max_f32_e32 v40, v40, v92
	s_mov_b64 exec, 1
	ds_write_b32 v48, v96 offset:1280
	v_max_f32_e32 v40, v40, v96
	s_mov_b64 exec, -1
	s_nop 4
	global_load_dwordx4 v[56:59], v49, s[76:77]
	s_sub_u32 s76, s76, 0x40000
	s_subb_u32 s77, s77, 0
	global_load_dwordx4 v[60:63], v49, s[76:77]
	s_sub_u32 s76, s76, 0x40000
	s_subb_u32 s77, s77, 0
	global_load_dwordx4 v[64:67], v49, s[76:77]
	s_sub_u32 s76, s76, 0x40000
	s_subb_u32 s77, s77, 0
	global_load_dwordx4 v[68:71], v49, s[76:77]
	s_sub_u32 s76, s76, 0x40000
	s_subb_u32 s77, s77, 0
	global_load_dwordx4 v[72:75], v49, s[76:77]
	s_sub_u32 s76, s76, 0x40000
	s_subb_u32 s77, s77, 0
	global_load_dwordx4 v[76:79], v49, s[76:77]
	s_sub_u32 s76, s76, 0x40000
	s_subb_u32 s77, s77, 0
	global_load_dwordx4 v[80:83], v49, s[76:77]
	s_sub_u32 s76, s76, 0x40000
	s_subb_u32 s77, s77, 0
	global_load_dwordx4 v[84:87], v49, s[76:77]
	s_sub_u32 s76, s76, 0x40000
	s_subb_u32 s77, s77, 0
	global_load_dwordx4 v[88:91], v49, s[76:77]
	s_sub_u32 s76, s76, 0x40000
	s_subb_u32 s77, s77, 0
	global_load_dwordx4 v[92:95], v49, s[76:77]
	s_sub_u32 s76, s76, 0x40000
	s_subb_u32 s77, s77, 0
	global_load_dwordx4 v[96:99], v49, s[76:77]
	s_sub_u32 s76, s76, 0x40000
	s_subb_u32 s77, s77, 0
	s_waitcnt vmcnt(11)
; #define LAS __attribute__((address_space(3)))
; DI float bflo(unsigned w) { return __uint_as_float(w << 16); }
; DI float bfhi(unsigned w) { return __uint_as_float(w & 0xffff0000u); }
; DI void attn_sample_unit(const Params& p, int u, const bf16_t* Q, const bf16_t* Kb, const bf16_t* Vb, bf16_t* att, LAS float* sl, int lane) {
;     ...
;     for (int e = 0; e < 9; ++e) { const int pat = e / 3, r = e - 3 * pat; const int dil = 1 << (2 * pat);
;         const int j = lane + 64 * r; const bool valid = j <= 128; const int idx = 2048 + t - dil * (valid ? j : 0);
;         float dot = 0.f;
;         if (idx >= 2048) { const bf16_t* kp = Kb + ((size_t)NP + b * 4 + (idx - 2048)) * 1024 + h * 64;
; #pragma unroll
;             for (int d8 = 0; d8 < 8; ++d8) { const u32x4 kw = *(const u32x4*)(kp + 8 * d8); const f32x4 q0 = *(const LAS f32x4*)(sl + 8 * d8), q1 = *(const LAS f32x4*)(sl + 8 * d8 + 4);
;                 dot += (bflo(kw.x) * q0[0] + bfhi(kw.x) * q0[1]) + (bflo(kw.y) * q0[2] + bfhi(kw.y) * q0[3]) + (bflo(kw.z) * q1[0] + bfhi(kw.z) * q1[1]) + (bflo(kw.w) * q1[2] + bfhi(kw.w) * q1[3]); } }
;         else { const float* kp = ck + (((size_t)b * 2048 + idx) * 16 + h) * 64;
; #pragma unroll
;             for (int d4 = 0; d4 < 16; ++d4) { const f32x4 kv = *(const f32x4*)(kp + 4 * d4); const f32x4 qv = *(const LAS f32x4*)(sl + 4 * d4); dot += (kv[0] * qv[0] + kv[1] * qv[1]) + (kv[2] * qv[2] + kv[3] * qv[3]); } }
;         if (valid) { sl[64 + pat * 192 + j] = dot; mx = fmaxf(mx, dot); } }
	v_mul_f32_e32 v0, v0, v44
	v_mul_f32_e32 v4, v4, v44
	v_mul_f32_e32 v8, v8, v44
	v_mul_f32_e32 v12, v12, v44
	v_mul_f32_e32 v16, v16, v44
	v_mul_f32_e32 v20, v20, v44
	v_mul_f32_e32 v24, v24, v44
	v_mul_f32_e32 v28, v28, v44
	v_mul_f32_e32 v32, v32, v44
	v_mul_f32_e32 v36, v36, v44
	v_mul_f32_e32 v52, v52, v44
	v_fmac_f32_e32 v0, v1, v45
	v_fmac_f32_e32 v4, v5, v45
	v_fmac_f32_e32 v8, v9, v45
	v_fmac_f32_e32 v12, v13, v45
	v_fmac_f32_e32 v16, v17, v45
	v_fmac_f32_e32 v20, v21, v45
	v_fmac_f32_e32 v24, v25, v45
	v_fmac_f32_e32 v28, v29, v45
	v_fmac_f32_e32 v32, v33, v45
	v_fmac_f32_e32 v36, v37, v45
	v_fmac_f32_e32 v52, v53, v45
	v_fmac_f32_e32 v0, v2, v46
	v_fmac_f32_e32 v4, v6, v46
	v_fmac_f32_e32 v8, v10, v46
	v_fmac_f32_e32 v12, v14, v46
	v_fmac_f32_e32 v16, v18, v46
	v_fmac_f32_e32 v20, v22, v46
	v_fmac_f32_e32 v24, v26, v46
	v_fmac_f32_e32 v28, v30, v46
	v_fmac_f32_e32 v32, v34, v46
	v_fmac_f32_e32 v36, v38, v46
	v_fmac_f32_e32 v52, v54, v46
	v_fmac_f32_e32 v0, v3, v47
	v_fmac_f32_e32 v4, v7, v47
	v_fmac_f32_e32 v8, v11, v47
	v_fmac_f32_e32 v12, v15, v47
	v_fmac_f32_e32 v16, v19, v47
	v_fmac_f32_e32 v20, v23, v47
	v_fmac_f32_e32 v24, v27, v47
	v_fmac_f32_e32 v28, v31, v47
	v_fmac_f32_e32 v32, v35, v47
	v_fmac_f32_e32 v36, v39, v47
	v_fmac_f32_e32 v52, v55, v47
	s_nop 1
	v_add_f32_dpp v0, v0, v0 quad_perm:[1,0,3,2] row_mask:0xf bank_mask:0xf
	v_add_f32_dpp v4, v4, v4 quad_perm:[1,0,3,2] row_mask:0xf bank_mask:0xf
	v_add_f32_dpp v8, v8, v8 quad_perm:[1,0,3,2] row_mask:0xf bank_mask:0xf
	v_add_f32_dpp v12, v12, v12 quad_perm:[1,0,3,2] row_mask:0xf bank_mask:0xf
	v_add_f32_dpp v16, v16, v16 quad_perm:[1,0,3,2] row_mask:0xf bank_mask:0xf
	v_add_f32_dpp v20, v20, v20 quad_perm:[1,0,3,2] row_mask:0xf bank_mask:0xf
	v_add_f32_dpp v24, v24, v24 quad_perm:[1,0,3,2] row_mask:0xf bank_mask:0xf
	v_add_f32_dpp v28, v28, v28 quad_perm:[1,0,3,2] row_mask:0xf bank_mask:0xf
	v_add_f32_dpp v32, v32, v32 quad_perm:[1,0,3,2] row_mask:0xf bank_mask:0xf
	v_add_f32_dpp v36, v36, v36 quad_perm:[1,0,3,2] row_mask:0xf bank_mask:0xf
	v_add_f32_dpp v52, v52, v52 quad_perm:[1,0,3,2] row_mask:0xf bank_mask:0xf
	s_nop 1
	v_add_f32_dpp v0, v0, v0 quad_perm:[2,3,0,1] row_mask:0xf bank_mask:0xf
	v_add_f32_dpp v4, v4, v4 quad_perm:[2,3,0,1] row_mask:0xf bank_mask:0xf
	v_add_f32_dpp v8, v8, v8 quad_perm:[2,3,0,1] row_mask:0xf bank_mask:0xf
	v_add_f32_dpp v12, v12, v12 quad_perm:[2,3,0,1] row_mask:0xf bank_mask:0xf
	v_add_f32_dpp v16, v16, v16 quad_perm:[2,3,0,1] row_mask:0xf bank_mask:0xf
	v_add_f32_dpp v20, v20, v20 quad_perm:[2,3,0,1] row_mask:0xf bank_mask:0xf
	v_add_f32_dpp v24, v24, v24 quad_perm:[2,3,0,1] row_mask:0xf bank_mask:0xf
	v_add_f32_dpp v28, v28, v28 quad_perm:[2,3,0,1] row_mask:0xf bank_mask:0xf
	v_add_f32_dpp v32, v32, v32 quad_perm:[2,3,0,1] row_mask:0xf bank_mask:0xf
	v_add_f32_dpp v36, v36, v36 quad_perm:[2,3,0,1] row_mask:0xf bank_mask:0xf
	v_add_f32_dpp v52, v52, v52 quad_perm:[2,3,0,1] row_mask:0xf bank_mask:0xf
	s_nop 1
	v_add_f32_dpp v0, v0, v0 row_half_mirror row_mask:0xf bank_mask:0xf
	v_add_f32_dpp v4, v4, v4 row_half_mirror row_mask:0xf bank_mask:0xf
	v_add_f32_dpp v8, v8, v8 row_half_mirror row_mask:0xf bank_mask:0xf
	v_add_f32_dpp v12, v12, v12 row_half_mirror row_mask:0xf bank_mask:0xf
	v_add_f32_dpp v16, v16, v16 row_half_mirror row_mask:0xf bank_mask:0xf
	v_add_f32_dpp v20, v20, v20 row_half_mirror row_mask:0xf bank_mask:0xf
	v_add_f32_dpp v24, v24, v24 row_half_mirror row_mask:0xf bank_mask:0xf
	v_add_f32_dpp v28, v28, v28 row_half_mirror row_mask:0xf bank_mask:0xf
	v_add_f32_dpp v32, v32, v32 row_half_mirror row_mask:0xf bank_mask:0xf
	v_add_f32_dpp v36, v36, v36 row_half_mirror row_mask:0xf bank_mask:0xf
	v_add_f32_dpp v52, v52, v52 row_half_mirror row_mask:0xf bank_mask:0xf
	s_nop 1
	v_add_f32_dpp v0, v0, v0 row_mirror row_mask:0xf bank_mask:0xf
	v_add_f32_dpp v4, v4, v4 row_mirror row_mask:0xf bank_mask:0xf
	v_add_f32_dpp v8, v8, v8 row_mirror row_mask:0xf bank_mask:0xf
	v_add_f32_dpp v12, v12, v12 row_mirror row_mask:0xf bank_mask:0xf
	v_add_f32_dpp v16, v16, v16 row_mirror row_mask:0xf bank_mask:0xf
	v_add_f32_dpp v20, v20, v20 row_mirror row_mask:0xf bank_mask:0xf
	v_add_f32_dpp v24, v24, v24 row_mirror row_mask:0xf bank_mask:0xf
	v_add_f32_dpp v28, v28, v28 row_mirror row_mask:0xf bank_mask:0xf
	v_add_f32_dpp v32, v32, v32 row_mirror row_mask:0xf bank_mask:0xf
	v_add_f32_dpp v36, v36, v36 row_mirror row_mask:0xf bank_mask:0xf
	v_add_f32_dpp v52, v52, v52 row_mirror row_mask:0xf bank_mask:0xf
	s_nop 1
	s_mov_b32 s82, 0x10000
	s_mov_b32 s83, 0x10001
	s_mov_b64 exec, s[82:83]
	ds_write_b32 v48, v0 offset:1536
	v_max_f32_e32 v40, v40, v0
	s_mov_b32 s82, 0x10001
	s_mov_b32 s83, 0x10001
	s_mov_b64 exec, s[82:83]
	ds_write_b32 v48, v4 offset:1552
	v_max_f32_e32 v40, v40, v4
	ds_write_b32 v48, v8 offset:1568
	v_max_f32_e32 v40, v40, v8
	ds_write_b32 v48, v12 offset:1584
	v_max_f32_e32 v40, v40, v12
	ds_write_b32 v48, v16 offset:1600
	v_max_f32_e32 v40, v40, v16
	ds_write_b32 v48, v20 offset:1616
	v_max_f32_e32 v40, v40, v20
	ds_write_b32 v48, v24 offset:1632
	v_max_f32_e32 v40, v40, v24
	ds_write_b32 v48, v28 offset:1648
	v_max_f32_e32 v40, v40, v28
	ds_write_b32 v48, v32 offset:1664
	v_max_f32_e32 v40, v40, v32
	ds_write_b32 v48, v36 offset:1680
	v_max_f32_e32 v40, v40, v36
	ds_write_b32 v48, v52 offset:1696
	v_max_f32_e32 v40, v40, v52
	s_mov_b64 exec, -1
	s_nop 4
	global_load_dwordx4 v[0:3], v49, s[76:77]
	s_sub_u32 s76, s76, 0x40000
	s_subb_u32 s77, s77, 0
	global_load_dwordx4 v[4:7], v49, s[76:77]
	s_sub_u32 s76, s76, 0x40000
	s_subb_u32 s77, s77, 0
	global_load_dwordx4 v[8:11], v49, s[76:77]
	s_sub_u32 s76, s76, 0x40000
	s_subb_u32 s77, s77, 0
	global_load_dwordx4 v[12:15], v49, s[76:77]
	s_sub_u32 s76, s76, 0x40000
	s_subb_u32 s77, s77, 0
	global_load_dwordx4 v[16:19], v49, s[76:77]
	s_sub_u32 s76, s76, 0x40000
	s_subb_u32 s77, s77, 0
	global_load_dwordx4 v[20:23], v49, s[76:77]
	s_sub_u32 s76, s76, 0x40000
	s_subb_u32 s77, s77, 0
	global_load_dwordx4 v[24:27], v49, s[76:77]
	s_sub_u32 s76, s76, 0x40000
	s_subb_u32 s77, s77, 0
	global_load_dwordx4 v[28:31], v49, s[76:77]
	s_sub_u32 s76, s76, 0x40000
	s_subb_u32 s77, s77, 0
	global_load_dwordx4 v[32:35], v49, s[76:77]
	s_sub_u32 s76, s76, 0x40000
	s_subb_u32 s77, s77, 0
	global_load_dwordx4 v[36:39], v49, s[76:77]
	s_sub_u32 s76, s76, 0x40000
	s_subb_u32 s77, s77, 0
	s_mov_b64 exec, 0xffff
	global_load_dwordx4 v[52:55], v49, s[76:77]
	s_mov_b64 exec, -1
	s_waitcnt vmcnt(11)
; #define LAS __attribute__((address_space(3)))
; DI float bflo(unsigned w) { return __uint_as_float(w << 16); }
; DI float bfhi(unsigned w) { return __uint_as_float(w & 0xffff0000u); }
; DI void attn_sample_unit(const Params& p, int u, const bf16_t* Q, const bf16_t* Kb, const bf16_t* Vb, bf16_t* att, LAS float* sl, int lane) {
;     ...
;     for (int e = 0; e < 9; ++e) { const int pat = e / 3, r = e - 3 * pat; const int dil = 1 << (2 * pat);
;         const int j = lane + 64 * r; const bool valid = j <= 128; const int idx = 2048 + t - dil * (valid ? j : 0);
;         float dot = 0.f;
;         if (idx >= 2048) { const bf16_t* kp = Kb + ((size_t)NP + b * 4 + (idx - 2048)) * 1024 + h * 64;
; #pragma unroll
;             for (int d8 = 0; d8 < 8; ++d8) { const u32x4 kw = *(const u32x4*)(kp + 8 * d8); const f32x4 q0 = *(const LAS f32x4*)(sl + 8 * d8), q1 = *(const LAS f32x4*)(sl + 8 * d8 + 4);
;                 dot += (bflo(kw.x) * q0[0] + bfhi(kw.x) * q0[1]) + (bflo(kw.y) * q0[2] + bfhi(kw.y) * q0[3]) + (bflo(kw.z) * q1[0] + bfhi(kw.z) * q1[1]) + (bflo(kw.w) * q1[2] + bfhi(kw.w) * q1[3]); } }
;         else { const float* kp = ck + (((size_t)b * 2048 + idx) * 16 + h) * 64;
; #pragma unroll
;             for (int d4 = 0; d4 < 16; ++d4) { const f32x4 kv = *(const f32x4*)(kp + 4 * d4); const f32x4 qv = *(const LAS f32x4*)(sl + 4 * d4); dot += (kv[0] * qv[0] + kv[1] * qv[1]) + (kv[2] * qv[2] + kv[3] * qv[3]); } }
;         if (valid) { sl[64 + pat * 192 + j] = dot; mx = fmaxf(mx, dot); } }
	v_mul_f32_e32 v56, v56, v44
	v_mul_f32_e32 v60, v60, v44
	v_mul_f32_e32 v64, v64, v44
	v_mul_f32_e32 v68, v68, v44
	v_mul_f32_e32 v72, v72, v44
	v_mul_f32_e32 v76, v76, v44
	v_mul_f32_e32 v80, v80, v44
	v_mul_f32_e32 v84, v84, v44
	v_mul_f32_e32 v88, v88, v44
	v_mul_f32_e32 v92, v92, v44
	v_mul_f32_e32 v96, v96, v44
	v_fmac_f32_e32 v56, v57, v45
	v_fmac_f32_e32 v60, v61, v45
	v_fmac_f32_e32 v64, v65, v45
	v_fmac_f32_e32 v68, v69, v45
	v_fmac_f32_e32 v72, v73, v45
	v_fmac_f32_e32 v76, v77, v45
	v_fmac_f32_e32 v80, v81, v45
	v_fmac_f32_e32 v84, v85, v45
	v_fmac_f32_e32 v88, v89, v45
	v_fmac_f32_e32 v92, v93, v45
	v_fmac_f32_e32 v96, v97, v45
	v_fmac_f32_e32 v56, v58, v46
	v_fmac_f32_e32 v60, v62, v46
	v_fmac_f32_e32 v64, v66, v46
	v_fmac_f32_e32 v68, v70, v46
	v_fmac_f32_e32 v72, v74, v46
	v_fmac_f32_e32 v76, v78, v46
	v_fmac_f32_e32 v80, v82, v46
	v_fmac_f32_e32 v84, v86, v46
	v_fmac_f32_e32 v88, v90, v46
	v_fmac_f32_e32 v92, v94, v46
	v_fmac_f32_e32 v96, v98, v46
	v_fmac_f32_e32 v56, v59, v47
	v_fmac_f32_e32 v60, v63, v47
	v_fmac_f32_e32 v64, v67, v47
	v_fmac_f32_e32 v68, v71, v47
	v_fmac_f32_e32 v72, v75, v47
	v_fmac_f32_e32 v76, v79, v47
	v_fmac_f32_e32 v80, v83, v47
	v_fmac_f32_e32 v84, v87, v47
	v_fmac_f32_e32 v88, v91, v47
	v_fmac_f32_e32 v92, v95, v47
	v_fmac_f32_e32 v96, v99, v47
	s_nop 1
	v_add_f32_dpp v56, v56, v56 quad_perm:[1,0,3,2] row_mask:0xf bank_mask:0xf
	v_add_f32_dpp v60, v60, v60 quad_perm:[1,0,3,2] row_mask:0xf bank_mask:0xf
	v_add_f32_dpp v64, v64, v64 quad_perm:[1,0,3,2] row_mask:0xf bank_mask:0xf
	v_add_f32_dpp v68, v68, v68 quad_perm:[1,0,3,2] row_mask:0xf bank_mask:0xf
	v_add_f32_dpp v72, v72, v72 quad_perm:[1,0,3,2] row_mask:0xf bank_mask:0xf
	v_add_f32_dpp v76, v76, v76 quad_perm:[1,0,3,2] row_mask:0xf bank_mask:0xf
	v_add_f32_dpp v80, v80, v80 quad_perm:[1,0,3,2] row_mask:0xf bank_mask:0xf
	v_add_f32_dpp v84, v84, v84 quad_perm:[1,0,3,2] row_mask:0xf bank_mask:0xf
	v_add_f32_dpp v88, v88, v88 quad_perm:[1,0,3,2] row_mask:0xf bank_mask:0xf
	v_add_f32_dpp v92, v92, v92 quad_perm:[1,0,3,2] row_mask:0xf bank_mask:0xf
	v_add_f32_dpp v96, v96, v96 quad_perm:[1,0,3,2] row_mask:0xf bank_mask:0xf
	s_nop 1
	v_add_f32_dpp v56, v56, v56 quad_perm:[2,3,0,1] row_mask:0xf bank_mask:0xf
	v_add_f32_dpp v60, v60, v60 quad_perm:[2,3,0,1] row_mask:0xf bank_mask:0xf
	v_add_f32_dpp v64, v64, v64 quad_perm:[2,3,0,1] row_mask:0xf bank_mask:0xf
	v_add_f32_dpp v68, v68, v68 quad_perm:[2,3,0,1] row_mask:0xf bank_mask:0xf
	v_add_f32_dpp v72, v72, v72 quad_perm:[2,3,0,1] row_mask:0xf bank_mask:0xf
	v_add_f32_dpp v76, v76, v76 quad_perm:[2,3,0,1] row_mask:0xf bank_mask:0xf
	v_add_f32_dpp v80, v80, v80 quad_perm:[2,3,0,1] row_mask:0xf bank_mask:0xf
	v_add_f32_dpp v84, v84, v84 quad_perm:[2,3,0,1] row_mask:0xf bank_mask:0xf
	v_add_f32_dpp v88, v88, v88 quad_perm:[2,3,0,1] row_mask:0xf bank_mask:0xf
	v_add_f32_dpp v92, v92, v92 quad_perm:[2,3,0,1] row_mask:0xf bank_mask:0xf
	v_add_f32_dpp v96, v96, v96 quad_perm:[2,3,0,1] row_mask:0xf bank_mask:0xf
	s_nop 1
	v_add_f32_dpp v56, v56, v56 row_half_mirror row_mask:0xf bank_mask:0xf
	v_add_f32_dpp v60, v60, v60 row_half_mirror row_mask:0xf bank_mask:0xf
	v_add_f32_dpp v64, v64, v64 row_half_mirror row_mask:0xf bank_mask:0xf
	v_add_f32_dpp v68, v68, v68 row_half_mirror row_mask:0xf bank_mask:0xf
	v_add_f32_dpp v72, v72, v72 row_half_mirror row_mask:0xf bank_mask:0xf
	v_add_f32_dpp v76, v76, v76 row_half_mirror row_mask:0xf bank_mask:0xf
	v_add_f32_dpp v80, v80, v80 row_half_mirror row_mask:0xf bank_mask:0xf
	v_add_f32_dpp v84, v84, v84 row_half_mirror row_mask:0xf bank_mask:0xf
	v_add_f32_dpp v88, v88, v88 row_half_mirror row_mask:0xf bank_mask:0xf
	v_add_f32_dpp v92, v92, v92 row_half_mirror row_mask:0xf bank_mask:0xf
	v_add_f32_dpp v96, v96, v96 row_half_mirror row_mask:0xf bank_mask:0xf
	s_nop 1
	v_add_f32_dpp v56, v56, v56 row_mirror row_mask:0xf bank_mask:0xf
	v_add_f32_dpp v60, v60, v60 row_mirror row_mask:0xf bank_mask:0xf
	v_add_f32_dpp v64, v64, v64 row_mirror row_mask:0xf bank_mask:0xf
	v_add_f32_dpp v68, v68, v68 row_mirror row_mask:0xf bank_mask:0xf
	v_add_f32_dpp v72, v72, v72 row_mirror row_mask:0xf bank_mask:0xf
	v_add_f32_dpp v76, v76, v76 row_mirror row_mask:0xf bank_mask:0xf
	v_add_f32_dpp v80, v80, v80 row_mirror row_mask:0xf bank_mask:0xf
	v_add_f32_dpp v84, v84, v84 row_mirror row_mask:0xf bank_mask:0xf
	v_add_f32_dpp v88, v88, v88 row_mirror row_mask:0xf bank_mask:0xf
	v_add_f32_dpp v92, v92, v92 row_mirror row_mask:0xf bank_mask:0xf
	v_add_f32_dpp v96, v96, v96 row_mirror row_mask:0xf bank_mask:0xf
	s_nop 1
	s_mov_b32 s82, 0x10001
	s_mov_b32 s83, 0x10001
	s_mov_b64 exec, s[82:83]
	ds_write_b32 v48, v56 offset:1712
	v_max_f32_e32 v40, v40, v56
	ds_write_b32 v48, v60 offset:1728
	v_max_f32_e32 v40, v40, v60
	ds_write_b32 v48, v64 offset:1744
	v_max_f32_e32 v40, v40, v64
	ds_write_b32 v48, v68 offset:1760
	v_max_f32_e32 v40, v40, v68
	ds_write_b32 v48, v72 offset:1776
	v_max_f32_e32 v40, v40, v72
	ds_write_b32 v48, v76 offset:1792
	v_max_f32_e32 v40, v40, v76
	ds_write_b32 v48, v80 offset:1808
	v_max_f32_e32 v40, v40, v80
	ds_write_b32 v48, v84 offset:1824
	v_max_f32_e32 v40, v40, v84
	ds_write_b32 v48, v88 offset:1840
	v_max_f32_e32 v40, v40, v88
	ds_write_b32 v48, v92 offset:1856
	v_max_f32_e32 v40, v40, v92
	ds_write_b32 v48, v96 offset:1872
	v_max_f32_e32 v40, v40, v96
	s_mov_b64 exec, -1
	s_nop 4
	s_waitcnt vmcnt(0)
; #define LAS __attribute__((address_space(3)))
; DI float bflo(unsigned w) { return __uint_as_float(w << 16); }
; DI float bfhi(unsigned w) { return __uint_as_float(w & 0xffff0000u); }
; DI void attn_sample_unit(const Params& p, int u, const bf16_t* Q, const bf16_t* Kb, const bf16_t* Vb, bf16_t* att, LAS float* sl, int lane) {
;     ...
;     for (int e = 0; e < 9; ++e) { const int pat = e / 3, r = e - 3 * pat; const int dil = 1 << (2 * pat);
;         const int j = lane + 64 * r; const bool valid = j <= 128; const int idx = 2048 + t - dil * (valid ? j : 0);
;         float dot = 0.f;
;         if (idx >= 2048) { const bf16_t* kp = Kb + ((size_t)NP + b * 4 + (idx - 2048)) * 1024 + h * 64;
; #pragma unroll
;             for (int d8 = 0; d8 < 8; ++d8) { const u32x4 kw = *(const u32x4*)(kp + 8 * d8); const f32x4 q0 = *(const LAS f32x4*)(sl + 8 * d8), q1 = *(const LAS f32x4*)(sl + 8 * d8 + 4);
;                 dot += (bflo(kw.x) * q0[0] + bfhi(kw.x) * q0[1]) + (bflo(kw.y) * q0[2] + bfhi(kw.y) * q0[3]) + (bflo(kw.z) * q1[0] + bfhi(kw.z) * q1[1]) + (bflo(kw.w) * q1[2] + bfhi(kw.w) * q1[3]); } }
;         else { const float* kp = ck + (((size_t)b * 2048 + idx) * 16 + h) * 64;
; #pragma unroll
;             for (int d4 = 0; d4 < 16; ++d4) { const f32x4 kv = *(const f32x4*)(kp + 4 * d4); const f32x4 qv = *(const LAS f32x4*)(sl + 4 * d4); dot += (kv[0] * qv[0] + kv[1] * qv[1]) + (kv[2] * qv[2] + kv[3] * qv[3]); } }
;         if (valid) { sl[64 + pat * 192 + j] = dot; mx = fmaxf(mx, dot); } }
;     mx = wave_max(mx);
	v_mul_f32_e32 v0, v0, v44
	v_mul_f32_e32 v4, v4, v44
	v_mul_f32_e32 v8, v8, v44
	v_mul_f32_e32 v12, v12, v44
	v_mul_f32_e32 v16, v16, v44
	v_mul_f32_e32 v20, v20, v44
	v_mul_f32_e32 v24, v24, v44
	v_mul_f32_e32 v28, v28, v44
	v_mul_f32_e32 v32, v32, v44
	v_mul_f32_e32 v36, v36, v44
	v_mul_f32_e32 v52, v52, v44
	v_fmac_f32_e32 v0, v1, v45
	v_fmac_f32_e32 v4, v5, v45
	v_fmac_f32_e32 v8, v9, v45
	v_fmac_f32_e32 v12, v13, v45
	v_fmac_f32_e32 v16, v17, v45
	v_fmac_f32_e32 v20, v21, v45
	v_fmac_f32_e32 v24, v25, v45
	v_fmac_f32_e32 v28, v29, v45
	v_fmac_f32_e32 v32, v33, v45
	v_fmac_f32_e32 v36, v37, v45
	v_fmac_f32_e32 v52, v53, v45
	v_fmac_f32_e32 v0, v2, v46
	v_fmac_f32_e32 v4, v6, v46
	v_fmac_f32_e32 v8, v10, v46
	v_fmac_f32_e32 v12, v14, v46
	v_fmac_f32_e32 v16, v18, v46
	v_fmac_f32_e32 v20, v22, v46
	v_fmac_f32_e32 v24, v26, v46
	v_fmac_f32_e32 v28, v30, v46
	v_fmac_f32_e32 v32, v34, v46
	v_fmac_f32_e32 v36, v38, v46
	v_fmac_f32_e32 v52, v54, v46
	v_fmac_f32_e32 v0, v3, v47
	v_fmac_f32_e32 v4, v7, v47
	v_fmac_f32_e32 v8, v11, v47
	v_fmac_f32_e32 v12, v15, v47
	v_fmac_f32_e32 v16, v19, v47
	v_fmac_f32_e32 v20, v23, v47
	v_fmac_f32_e32 v24, v27, v47
	v_fmac_f32_e32 v28, v31, v47
	v_fmac_f32_e32 v32, v35, v47
	v_fmac_f32_e32 v36, v39, v47
	v_fmac_f32_e32 v52, v55, v47
	s_nop 1
	v_add_f32_dpp v0, v0, v0 quad_perm:[1,0,3,2] row_mask:0xf bank_mask:0xf
	v_add_f32_dpp v4, v4, v4 quad_perm:[1,0,3,2] row_mask:0xf bank_mask:0xf
	v_add_f32_dpp v8, v8, v8 quad_perm:[1,0,3,2] row_mask:0xf bank_mask:0xf
	v_add_f32_dpp v12, v12, v12 quad_perm:[1,0,3,2] row_mask:0xf bank_mask:0xf
	v_add_f32_dpp v16, v16, v16 quad_perm:[1,0,3,2] row_mask:0xf bank_mask:0xf
	v_add_f32_dpp v20, v20, v20 quad_perm:[1,0,3,2] row_mask:0xf bank_mask:0xf
	v_add_f32_dpp v24, v24, v24 quad_perm:[1,0,3,2] row_mask:0xf bank_mask:0xf
	v_add_f32_dpp v28, v28, v28 quad_perm:[1,0,3,2] row_mask:0xf bank_mask:0xf
	v_add_f32_dpp v32, v32, v32 quad_perm:[1,0,3,2] row_mask:0xf bank_mask:0xf
	v_add_f32_dpp v36, v36, v36 quad_perm:[1,0,3,2] row_mask:0xf bank_mask:0xf
	v_add_f32_dpp v52, v52, v52 quad_perm:[1,0,3,2] row_mask:0xf bank_mask:0xf
	s_nop 1
	v_add_f32_dpp v0, v0, v0 quad_perm:[2,3,0,1] row_mask:0xf bank_mask:0xf
	v_add_f32_dpp v4, v4, v4 quad_perm:[2,3,0,1] row_mask:0xf bank_mask:0xf
	v_add_f32_dpp v8, v8, v8 quad_perm:[2,3,0,1] row_mask:0xf bank_mask:0xf
	v_add_f32_dpp v12, v12, v12 quad_perm:[2,3,0,1] row_mask:0xf bank_mask:0xf
	v_add_f32_dpp v16, v16, v16 quad_perm:[2,3,0,1] row_mask:0xf bank_mask:0xf
	v_add_f32_dpp v20, v20, v20 quad_perm:[2,3,0,1] row_mask:0xf bank_mask:0xf
	v_add_f32_dpp v24, v24, v24 quad_perm:[2,3,0,1] row_mask:0xf bank_mask:0xf
	v_add_f32_dpp v28, v28, v28 quad_perm:[2,3,0,1] row_mask:0xf bank_mask:0xf
	v_add_f32_dpp v32, v32, v32 quad_perm:[2,3,0,1] row_mask:0xf bank_mask:0xf
	v_add_f32_dpp v36, v36, v36 quad_perm:[2,3,0,1] row_mask:0xf bank_mask:0xf
	v_add_f32_dpp v52, v52, v52 quad_perm:[2,3,0,1] row_mask:0xf bank_mask:0xf
	s_nop 1
	v_add_f32_dpp v0, v0, v0 row_half_mirror row_mask:0xf bank_mask:0xf
	v_add_f32_dpp v4, v4, v4 row_half_mirror row_mask:0xf bank_mask:0xf
	v_add_f32_dpp v8, v8, v8 row_half_mirror row_mask:0xf bank_mask:0xf
	v_add_f32_dpp v12, v12, v12 row_half_mirror row_mask:0xf bank_mask:0xf
	v_add_f32_dpp v16, v16, v16 row_half_mirror row_mask:0xf bank_mask:0xf
	v_add_f32_dpp v20, v20, v20 row_half_mirror row_mask:0xf bank_mask:0xf
	v_add_f32_dpp v24, v24, v24 row_half_mirror row_mask:0xf bank_mask:0xf
	v_add_f32_dpp v28, v28, v28 row_half_mirror row_mask:0xf bank_mask:0xf
	v_add_f32_dpp v32, v32, v32 row_half_mirror row_mask:0xf bank_mask:0xf
	v_add_f32_dpp v36, v36, v36 row_half_mirror row_mask:0xf bank_mask:0xf
	v_add_f32_dpp v52, v52, v52 row_half_mirror row_mask:0xf bank_mask:0xf
	s_nop 1
	v_add_f32_dpp v0, v0, v0 row_mirror row_mask:0xf bank_mask:0xf
	v_add_f32_dpp v4, v4, v4 row_mirror row_mask:0xf bank_mask:0xf
	v_add_f32_dpp v8, v8, v8 row_mirror row_mask:0xf bank_mask:0xf
	v_add_f32_dpp v12, v12, v12 row_mirror row_mask:0xf bank_mask:0xf
	v_add_f32_dpp v16, v16, v16 row_mirror row_mask:0xf bank_mask:0xf
	v_add_f32_dpp v20, v20, v20 row_mirror row_mask:0xf bank_mask:0xf
	v_add_f32_dpp v24, v24, v24 row_mirror row_mask:0xf bank_mask:0xf
	v_add_f32_dpp v28, v28, v28 row_mirror row_mask:0xf bank_mask:0xf
	v_add_f32_dpp v32, v32, v32 row_mirror row_mask:0xf bank_mask:0xf
	v_add_f32_dpp v36, v36, v36 row_mirror row_mask:0xf bank_mask:0xf
	v_add_f32_dpp v52, v52, v52 row_mirror row_mask:0xf bank_mask:0xf
	s_nop 1
	s_mov_b32 s82, 0x10001
	s_mov_b32 s83, 0x10001
	s_mov_b64 exec, s[82:83]
	ds_write_b32 v48, v0 offset:1888
	v_max_f32_e32 v40, v40, v0
	ds_write_b32 v48, v4 offset:1904
	v_max_f32_e32 v40, v40, v4
	ds_write_b32 v48, v8 offset:1920
	v_max_f32_e32 v40, v40, v8
	ds_write_b32 v48, v12 offset:1936
	v_max_f32_e32 v40, v40, v12
	ds_write_b32 v48, v16 offset:1952
	v_max_f32_e32 v40, v40, v16
	ds_write_b32 v48, v20 offset:1968
	v_max_f32_e32 v40, v40, v20
	ds_write_b32 v48, v24 offset:1984
	v_max_f32_e32 v40, v40, v24
	ds_write_b32 v48, v28 offset:2000
	v_max_f32_e32 v40, v40, v28
	ds_write_b32 v48, v32 offset:2016
	v_max_f32_e32 v40, v40, v32
	ds_write_b32 v48, v36 offset:2032
	v_max_f32_e32 v40, v40, v36
	s_mov_b64 exec, 1
	ds_write_b32 v48, v52 offset:2048
	v_max_f32_e32 v40, v40, v52
	s_mov_b64 exec, -1
	s_nop 4
	s_waitcnt vmcnt(0) lgkmcnt(0)
